# plain (non-NORM) MTW=4 GEMM loops of the two residual phases restructured like the NORM loops (immediate reload after LDS write, pipelined MFMA phase)
# speedup vs baseline: 1.0144x; 1.0034x over previous
; DI int TID() { int t = threadIdx.x; asm volatile("" : "+v"(t)); return t; }
; #define ZERO_ACCM(a, MT) _Pragma("unroll") for (int _m = 0; _m < MT; ++_m) _Pragma("unroll") for (int _n = 0; _n < 2; ++_n) _Pragma("unroll") for (int _i = 0; _i < 16; ++_i) a[_m][_n][_i] = 0.f;
; template <bool NORM, bool DEEP, int MTW, int KSEG, class HOOK>
; DI void gemm_core_h(const bfu* __restrict__ A, int lda, const bfu* __restrict__ Bt, int ldb, int K, int m0, int n0,
;                     f32x16 (&acc)[MTW][2], char* smem, HOOK hook) {
;     ...
;   const int tid = TID(), lane = tid & 63, w = tid >> 6, r = lane & 31, hh = lane >> 5;
;   const int wm = w >> 1, wn = w & 1;
;   const int lrow = tid >> 3, lkc = tid & 7;
;   const unsigned aoff = (unsigned)((m0 + lrow) * lda + lkc * 8);
;   const unsigned boff = (unsigned)((n0 + lrow) * ldb + lkc * 8);
;     ...
;   u32x4 ra0[NA], rb0[4], ra1[NA], rb1[4];
;   float ssq[NA];
; #pragma unroll
;   for (int j = 0; j < NA; ++j) ssq[j] = 0.f;
;   const int nk = K >> 6;
; #pragma unroll
;   for (int j = 0; j < NA; ++j) ra0[j] = *(const u32x4*)AP_(j, 0);
; #pragma unroll
;   for (int j = 0; j < 4; ++j) rb0[j] = *(const u32x4*)BP_(j, 0);
; DI void phase_resid(const Params& p, const bfu* A, int lda, const bfu* Bt, int K, char* smem) {
;     ...
;   for (int id = blockIdx.x; id < 64 * 8; id += gridDim.x) {
;     int tm, tn; map_tile(id, 8, tm, tn);
;     const int m0 = tm * 256, n0 = tn * 128;
;     f32x16 acc[4][2]; ZERO_ACCM(acc, 4)
;     gemm_core<false, false, 4>(A, lda, Bt, K, K, m0, n0, acc, smem);
.LBB0_95:
	s_ashr_i32 s4, s2, 31
	s_ashr_i32 s3, s2, 3
	s_lshr_b32 s4, s4, 26
	s_add_i32 s4, s3, s4
	s_andn2_b32 s4, s4, 63
	s_lshl_b32 s6, s2, 3
	s_sub_i32 s3, s3, s4
	s_and_b32 s6, s6, 56
	s_and_b32 s5, s3, 7
	s_or_b32 s4, s4, s6
	s_or_b32 s4, s4, s5
	s_lshl_b32 s5, s3, 4
	v_mov_b32_e32 v4, v224
	s_lshl_b32 s3, s4, 8
	s_and_b32 s4, s5, 0xffffff80
	v_readlane_b32 s16, v253, 48
	v_ashrrev_i32_e32 v5, 3, v4
	v_lshlrev_b32_e32 v1, 3, v4
	v_and_b32_e32 v6, 56, v1
	v_add_u32_e32 v1, s4, v5
	v_lshl_or_b32 v178, v1, 12, v6
	v_add_u32_e32 v0, s3, v5
	v_add_u32_e32 v188, 0x60000, v178
	v_readlane_b32 s26, v253, 58
	v_readlane_b32 s27, v253, 59
	v_lshl_or_b32 v176, v0, 12, v6
	v_mov_b32_e32 v179, v189
	v_lshl_add_u64 v[0:1], v[188:189], 1, s[26:27]
	v_add_u32_e32 v188, 0x40000, v178
	v_lshl_add_u64 v[2:3], v[188:189], 1, s[26:27]
	v_add_u32_e32 v188, 0x20000, v178
	global_load_dwordx4 v[132:135], v[0:1], off
	global_load_dwordx4 v[128:131], v[2:3], off
	v_lshl_add_u64 v[0:1], v[188:189], 1, s[26:27]
	v_lshl_add_u64 v[2:3], v[178:179], 1, s[26:27]
	v_mov_b32_e32 v177, v189
	v_add_u32_e32 v188, 0x20000, v176
	global_load_dwordx4 v[136:139], v[0:1], off
	global_load_dwordx4 v[140:143], v[2:3], off
	v_lshl_add_u64 v[0:1], v[176:177], 1, s[72:73]
	v_lshl_add_u64 v[2:3], v[188:189], 1, s[72:73]
	v_add_u32_e32 v188, 0x40000, v176
	global_load_dwordx4 v[148:151], v[0:1], off
	global_load_dwordx4 v[144:147], v[2:3], off
	v_lshl_add_u64 v[0:1], v[188:189], 1, s[72:73]
	v_add_u32_e32 v188, 0x60000, v176
	v_lshl_add_u64 v[2:3], v[188:189], 1, s[72:73]
	v_add_u32_e32 v188, 0x80000, v176
	global_load_dwordx4 v[156:159], v[0:1], off
	global_load_dwordx4 v[152:155], v[2:3], off
	v_lshl_add_u64 v[0:1], v[188:189], 1, s[72:73]
	v_add_u32_e32 v188, 0xa0000, v176
	v_lshl_add_u64 v[2:3], v[188:189], 1, s[72:73]
	v_add_u32_e32 v188, 0xc0000, v176
	global_load_dwordx4 v[164:167], v[0:1], off
	global_load_dwordx4 v[160:163], v[2:3], off
	v_lshl_add_u64 v[0:1], v[188:189], 1, s[72:73]
	v_add_u32_e32 v188, 0xe0000, v176
	v_lshl_add_u64 v[2:3], v[188:189], 1, s[72:73]
	global_load_dwordx4 v[168:171], v[0:1], off
	global_load_dwordx4 v[172:175], v[2:3], off
	v_lshrrev_b32_e32 v2, 1, v4
	v_and_b32_e32 v0, 0x5f, v4
	v_and_b32_e32 v2, 16, v2
	s_movk_i32 s5, 0x90
	v_mad_u32_u24 v182, v0, s5, v2
	v_and_b32_e32 v0, 0xfffff9f, v4
	v_mul_lo_u32 v3, v0, s5
	v_or_b32_e32 v0, 0x60, v4
	v_lshlrev_b32_e32 v1, 1, v6
	v_mul_lo_u32 v5, v5, s5
	v_mul_lo_u32 v4, v0, s5
	v_mov_b32_e32 v0, 0
	s_mov_b32 s5, 0
	v_add_u32_e32 v183, v1, v5
	v_add_u32_e32 v179, v2, v3
	v_add_u32_e32 v177, v2, v4
	v_mov_b32_e32 v1, v0
	v_mov_b32_e32 v2, v0
	v_mov_b32_e32 v3, v0
	v_mov_b32_e32 v4, v0
	v_mov_b32_e32 v5, v0
	v_mov_b32_e32 v6, v0
	v_mov_b32_e32 v7, v0
	v_mov_b32_e32 v8, v0
	v_mov_b32_e32 v9, v0
	v_mov_b32_e32 v10, v0
	v_mov_b32_e32 v11, v0
	v_mov_b32_e32 v12, v0
	v_mov_b32_e32 v13, v0
	v_mov_b32_e32 v14, v0
	v_mov_b32_e32 v15, v0
	v_mov_b32_e32 v16, v0
	v_mov_b32_e32 v17, v0
	v_mov_b32_e32 v18, v0
	v_mov_b32_e32 v19, v0
	v_mov_b32_e32 v20, v0
	v_mov_b32_e32 v21, v0
	v_mov_b32_e32 v22, v0
	v_mov_b32_e32 v23, v0
	v_mov_b32_e32 v24, v0
	v_mov_b32_e32 v25, v0
	v_mov_b32_e32 v26, v0
	v_mov_b32_e32 v27, v0
	v_mov_b32_e32 v28, v0
	v_mov_b32_e32 v29, v0
	v_mov_b32_e32 v30, v0
	v_mov_b32_e32 v31, v0
	v_mov_b32_e32 v32, v0
	v_mov_b32_e32 v33, v0
	v_mov_b32_e32 v34, v0
	v_mov_b32_e32 v35, v0
	v_mov_b32_e32 v36, v0
	v_mov_b32_e32 v37, v0
	v_mov_b32_e32 v38, v0
	v_mov_b32_e32 v39, v0
	v_mov_b32_e32 v40, v0
	v_mov_b32_e32 v41, v0
	v_mov_b32_e32 v42, v0
	v_mov_b32_e32 v43, v0
	v_mov_b32_e32 v44, v0
	v_mov_b32_e32 v45, v0
	v_mov_b32_e32 v46, v0
	v_mov_b32_e32 v47, v0
	v_mov_b32_e32 v48, v0
	v_mov_b32_e32 v49, v0
	v_mov_b32_e32 v50, v0
	v_mov_b32_e32 v51, v0
	v_mov_b32_e32 v52, v0
	v_mov_b32_e32 v53, v0
	v_mov_b32_e32 v54, v0
	v_mov_b32_e32 v55, v0
	v_mov_b32_e32 v56, v0
	v_mov_b32_e32 v57, v0
	v_mov_b32_e32 v58, v0
	v_mov_b32_e32 v59, v0
	v_mov_b32_e32 v60, v0
	v_mov_b32_e32 v61, v0
	v_mov_b32_e32 v62, v0
	v_mov_b32_e32 v63, v0
	v_mov_b32_e32 v64, v0
	v_mov_b32_e32 v65, v0
	v_mov_b32_e32 v66, v0
	v_mov_b32_e32 v67, v0
	v_mov_b32_e32 v68, v0
	v_mov_b32_e32 v69, v0
	v_mov_b32_e32 v70, v0
	v_mov_b32_e32 v71, v0
	s_waitcnt vmcnt(17)
	v_mov_b32_e32 v72, v0
	v_mov_b32_e32 v73, v0
	v_mov_b32_e32 v74, v0
	v_mov_b32_e32 v75, v0
	s_waitcnt vmcnt(16)
	v_mov_b32_e32 v76, v0
	v_mov_b32_e32 v77, v0
	v_mov_b32_e32 v78, v0
	v_mov_b32_e32 v79, v0
	s_waitcnt vmcnt(14)
	v_mov_b32_e32 v80, v0
	v_mov_b32_e32 v81, v0
	v_mov_b32_e32 v82, v0
	v_mov_b32_e32 v83, v0
	v_mov_b32_e32 v84, v0
	v_mov_b32_e32 v85, v0
	v_mov_b32_e32 v86, v0
	v_mov_b32_e32 v87, v0
	s_waitcnt vmcnt(13)
	v_mov_b32_e32 v88, v0
	v_mov_b32_e32 v89, v0
	v_mov_b32_e32 v90, v0
	v_mov_b32_e32 v91, v0
	s_waitcnt vmcnt(12)
	v_mov_b32_e32 v92, v0
	v_mov_b32_e32 v93, v0
	v_mov_b32_e32 v94, v0
	v_mov_b32_e32 v95, v0
	v_mov_b32_e32 v96, v0
	v_mov_b32_e32 v97, v0
	v_mov_b32_e32 v98, v0
	v_mov_b32_e32 v99, v0
	v_mov_b32_e32 v100, v0
	v_mov_b32_e32 v101, v0
	v_mov_b32_e32 v102, v0
	v_mov_b32_e32 v103, v0
	v_mov_b32_e32 v104, v0
	v_mov_b32_e32 v105, v0
	v_mov_b32_e32 v106, v0
	v_mov_b32_e32 v107, v0
	v_mov_b32_e32 v108, v0
	v_mov_b32_e32 v109, v0
	v_mov_b32_e32 v110, v0
	v_mov_b32_e32 v111, v0
	v_mov_b32_e32 v112, v0
	v_mov_b32_e32 v113, v0
	v_mov_b32_e32 v114, v0
	v_mov_b32_e32 v115, v0
	v_mov_b32_e32 v116, v0
	v_mov_b32_e32 v117, v0
	v_mov_b32_e32 v118, v0
	v_mov_b32_e32 v119, v0
	v_mov_b32_e32 v120, v0
	v_mov_b32_e32 v121, v0
	v_mov_b32_e32 v122, v0
	v_mov_b32_e32 v123, v0
	v_mov_b32_e32 v124, v0
	v_mov_b32_e32 v125, v0
	v_mov_b32_e32 v126, v0
	v_mov_b32_e32 v127, v0
	v_readlane_b32 s17, v253, 49
	v_readlane_b32 s18, v253, 50
	v_readlane_b32 s19, v253, 51
	v_readlane_b32 s20, v253, 52
	v_readlane_b32 s21, v253, 53
	v_readlane_b32 s22, v253, 54
	v_readlane_b32 s23, v253, 55
	v_readlane_b32 s24, v253, 56
	v_readlane_b32 s25, v253, 57
	v_readlane_b32 s28, v253, 60
	v_readlane_b32 s29, v253, 61
	v_readlane_b32 s30, v253, 62
	v_readlane_b32 s31, v253, 63
	s_waitcnt vmcnt(0)
; template <bool NORM, bool DEEP, int MTW, int KSEG, class HOOK>
; DI void gemm_core_h(const bfu* __restrict__ A, int lda, const bfu* __restrict__ Bt, int ldb, int K, int m0, int n0,
;                     f32x16 (&acc)[MTW][2], char* smem, HOOK hook) {
;     ...
;   if (DEEP) {
;     for (int kt = 0; kt < nk; kt += 2) {
;       GEMM_STEP(ra0, rb0, kt, 2)
;       GEMM_STEP(ra1, rb1, kt + 1, 2)
;     }
;   } else {
;     for (int kt = 0; kt < nk; ++kt) {
;       GEMM_STEP(ra0, rb0, kt, 1)
.LBB0_96:
	s_waitcnt lgkmcnt(0)
	s_barrier
	s_waitcnt vmcnt(11)
	ds_write_b128 v183, v[140:143] offset:36864
	v_add_u32_e32 v188, s5, v178
	v_add_u32_e32 v188, 0x40, v188
	v_lshl_add_u64 v[140:141], v[188:189], 1, s[26:27]
	global_load_dwordx4 v[140:143], v[140:141], off
	s_waitcnt vmcnt(11)
	ds_write_b128 v183, v[136:139] offset:41472
	v_add_u32_e32 v188, s5, v178
	v_add_u32_e32 v188, 0x20040, v188
	v_lshl_add_u64 v[136:137], v[188:189], 1, s[26:27]
	global_load_dwordx4 v[136:139], v[136:137], off
	s_waitcnt vmcnt(11)
	ds_write_b128 v183, v[128:131] offset:46080
	v_add_u32_e32 v188, s5, v178
	v_add_u32_e32 v188, 0x40040, v188
	v_lshl_add_u64 v[128:129], v[188:189], 1, s[26:27]
	global_load_dwordx4 v[128:131], v[128:129], off
	s_waitcnt vmcnt(11)
	ds_write_b128 v183, v[132:135] offset:50688
	v_add_u32_e32 v188, s5, v178
	v_add_u32_e32 v188, 0x60040, v188
	v_lshl_add_u64 v[132:133], v[188:189], 1, s[26:27]
	global_load_dwordx4 v[132:135], v[132:133], off
	s_waitcnt vmcnt(11)
	ds_write_b128 v183, v[148:151]
	v_add_u32_e32 v188, s5, v176
	v_add_u32_e32 v188, 0x40, v188
	v_lshl_add_u64 v[148:149], v[188:189], 1, s[72:73]
	global_load_dwordx4 v[148:151], v[148:149], off
	s_waitcnt vmcnt(11)
	ds_write_b128 v183, v[144:147] offset:4608
	v_add_u32_e32 v188, s5, v176
	v_add_u32_e32 v188, 0x20040, v188
	v_lshl_add_u64 v[144:145], v[188:189], 1, s[72:73]
	global_load_dwordx4 v[144:147], v[144:145], off
	s_waitcnt vmcnt(11)
	ds_write_b128 v183, v[156:159] offset:9216
	v_add_u32_e32 v188, s5, v176
	v_add_u32_e32 v188, 0x40040, v188
	v_lshl_add_u64 v[156:157], v[188:189], 1, s[72:73]
	global_load_dwordx4 v[156:159], v[156:157], off
	s_waitcnt vmcnt(11)
	ds_write_b128 v183, v[152:155] offset:13824
	v_add_u32_e32 v188, s5, v176
	v_add_u32_e32 v188, 0x60040, v188
	v_lshl_add_u64 v[152:153], v[188:189], 1, s[72:73]
	global_load_dwordx4 v[152:155], v[152:153], off
	s_waitcnt vmcnt(11)
	ds_write_b128 v183, v[164:167] offset:18432
	v_add_u32_e32 v188, s5, v176
	v_add_u32_e32 v188, 0x80040, v188
	v_lshl_add_u64 v[164:165], v[188:189], 1, s[72:73]
	global_load_dwordx4 v[164:167], v[164:165], off
	s_waitcnt vmcnt(11)
	ds_write_b128 v183, v[160:163] offset:23040
	v_add_u32_e32 v188, s5, v176
	v_add_u32_e32 v188, 0xa0040, v188
	v_lshl_add_u64 v[160:161], v[188:189], 1, s[72:73]
	global_load_dwordx4 v[160:163], v[160:161], off
	s_waitcnt vmcnt(11)
	ds_write_b128 v183, v[168:171] offset:27648
	v_add_u32_e32 v188, s5, v176
	v_add_u32_e32 v188, 0xc0040, v188
	v_lshl_add_u64 v[168:169], v[188:189], 1, s[72:73]
	global_load_dwordx4 v[168:171], v[168:169], off
	s_waitcnt vmcnt(11)
	ds_write_b128 v183, v[172:175] offset:32256
	v_add_u32_e32 v188, s5, v176
	v_add_u32_e32 v188, 0xe0040, v188
	v_lshl_add_u64 v[172:173], v[188:189], 1, s[72:73]
	global_load_dwordx4 v[172:175], v[172:173], off
	s_waitcnt lgkmcnt(0)
	s_barrier
	ds_read_b128 v[202:205], v182 offset:36864
	ds_read_b128 v[206:209], v182 offset:41472
	ds_read_b128 v[218:221], v179
	ds_read_b128 v[232:235], v179 offset:4608
	s_waitcnt lgkmcnt(1)
	v_mfma_f32_32x32x16_bf16 v[112:127], v[218:221], v[202:205], v[112:127]
	v_mfma_f32_32x32x16_bf16 v[96:111], v[218:221], v[206:209], v[96:111]
	ds_read_b128 v[218:221], v179 offset:9216
	s_waitcnt lgkmcnt(1)
	v_mfma_f32_32x32x16_bf16 v[80:95], v[232:235], v[202:205], v[80:95]
	v_mfma_f32_32x32x16_bf16 v[64:79], v[232:235], v[206:209], v[64:79]
	ds_read_b128 v[232:235], v177
	ds_read_b128 v[210:213], v182 offset:36896
	ds_read_b128 v[214:217], v182 offset:41504
	s_waitcnt lgkmcnt(3)
	v_mfma_f32_32x32x16_bf16 v[48:63], v[218:221], v[202:205], v[48:63]
	v_mfma_f32_32x32x16_bf16 v[32:47], v[218:221], v[206:209], v[32:47]
	ds_read_b128 v[218:221], v179 offset:32
	s_waitcnt lgkmcnt(3)
	v_mfma_f32_32x32x16_bf16 v[16:31], v[232:235], v[202:205], v[16:31]
	v_mfma_f32_32x32x16_bf16 v[0:15], v[232:235], v[206:209], v[0:15]
	ds_read_b128 v[232:235], v179 offset:4640
	s_waitcnt lgkmcnt(1)
	v_mfma_f32_32x32x16_bf16 v[112:127], v[218:221], v[210:213], v[112:127]
	v_mfma_f32_32x32x16_bf16 v[96:111], v[218:221], v[214:217], v[96:111]
	ds_read_b128 v[218:221], v179 offset:9248
	s_waitcnt lgkmcnt(1)
	v_mfma_f32_32x32x16_bf16 v[80:95], v[232:235], v[210:213], v[80:95]
	v_mfma_f32_32x32x16_bf16 v[64:79], v[232:235], v[214:217], v[64:79]
	ds_read_b128 v[232:235], v177 offset:32
	ds_read_b128 v[202:205], v182 offset:36928
	ds_read_b128 v[206:209], v182 offset:41536
	s_waitcnt lgkmcnt(3)
	v_mfma_f32_32x32x16_bf16 v[48:63], v[218:221], v[210:213], v[48:63]
	v_mfma_f32_32x32x16_bf16 v[32:47], v[218:221], v[214:217], v[32:47]
	ds_read_b128 v[218:221], v179 offset:64
	s_waitcnt lgkmcnt(3)
	v_mfma_f32_32x32x16_bf16 v[16:31], v[232:235], v[210:213], v[16:31]
	v_mfma_f32_32x32x16_bf16 v[0:15], v[232:235], v[214:217], v[0:15]
	ds_read_b128 v[232:235], v179 offset:4672
	s_waitcnt lgkmcnt(1)
	v_mfma_f32_32x32x16_bf16 v[112:127], v[218:221], v[202:205], v[112:127]
	v_mfma_f32_32x32x16_bf16 v[96:111], v[218:221], v[206:209], v[96:111]
	ds_read_b128 v[218:221], v179 offset:9280
	s_waitcnt lgkmcnt(1)
	v_mfma_f32_32x32x16_bf16 v[80:95], v[232:235], v[202:205], v[80:95]
	v_mfma_f32_32x32x16_bf16 v[64:79], v[232:235], v[206:209], v[64:79]
	ds_read_b128 v[232:235], v177 offset:64
	ds_read_b128 v[210:213], v182 offset:36960
	ds_read_b128 v[214:217], v182 offset:41568
	s_waitcnt lgkmcnt(3)
	v_mfma_f32_32x32x16_bf16 v[48:63], v[218:221], v[202:205], v[48:63]
	v_mfma_f32_32x32x16_bf16 v[32:47], v[218:221], v[206:209], v[32:47]
	ds_read_b128 v[218:221], v179 offset:96
	s_waitcnt lgkmcnt(3)
	v_mfma_f32_32x32x16_bf16 v[16:31], v[232:235], v[202:205], v[16:31]
	v_mfma_f32_32x32x16_bf16 v[0:15], v[232:235], v[206:209], v[0:15]
	ds_read_b128 v[232:235], v179 offset:4704
	s_waitcnt lgkmcnt(1)
	v_mfma_f32_32x32x16_bf16 v[112:127], v[218:221], v[210:213], v[112:127]
	v_mfma_f32_32x32x16_bf16 v[96:111], v[218:221], v[214:217], v[96:111]
	ds_read_b128 v[218:221], v179 offset:9312
	s_waitcnt lgkmcnt(1)
	v_mfma_f32_32x32x16_bf16 v[80:95], v[232:235], v[210:213], v[80:95]
	v_mfma_f32_32x32x16_bf16 v[64:79], v[232:235], v[214:217], v[64:79]
	ds_read_b128 v[232:235], v177 offset:96
	s_waitcnt lgkmcnt(1)
	v_mfma_f32_32x32x16_bf16 v[48:63], v[218:221], v[210:213], v[48:63]
	v_mfma_f32_32x32x16_bf16 v[32:47], v[218:221], v[214:217], v[32:47]
	s_waitcnt lgkmcnt(0)
	v_mfma_f32_32x32x16_bf16 v[16:31], v[232:235], v[210:213], v[16:31]
	v_mfma_f32_32x32x16_bf16 v[0:15], v[232:235], v[214:217], v[0:15]
	s_add_i32 s5, s5, 64
	s_cmpk_lg_i32 s5, 0xfc0
	s_cbranch_scc1 .LBB0_96
; template <bool NORM, bool DEEP, int MTW, int KSEG, class HOOK>
; DI void gemm_core_h(const bfu* __restrict__ A, int lda, const bfu* __restrict__ Bt, int ldb, int K, int m0, int n0,
;                     f32x16 (&acc)[MTW][2], char* smem, HOOK hook) {
;     ...
;   if (DEEP) {
;     for (int kt = 0; kt < nk; kt += 2) {
;       GEMM_STEP(ra0, rb0, kt, 2)
;       GEMM_STEP(ra1, rb1, kt + 1, 2)
;     }
;   } else {
;     for (int kt = 0; kt < nk; ++kt) {
;       GEMM_STEP(ra0, rb0, kt, 1)
	s_waitcnt vmcnt(0)
	s_waitcnt lgkmcnt(0)
	s_barrier
	s_waitcnt vmcnt(11)
	ds_write_b128 v183, v[148:151]
	s_waitcnt vmcnt(10)
	ds_write_b128 v183, v[144:147] offset:4608
	s_waitcnt vmcnt(9)
	ds_write_b128 v183, v[156:159] offset:9216
	s_waitcnt vmcnt(8)
	ds_write_b128 v183, v[152:155] offset:13824
	s_waitcnt vmcnt(7)
	ds_write_b128 v183, v[164:167] offset:18432
	s_waitcnt vmcnt(6)
	ds_write_b128 v183, v[160:163] offset:23040
	s_waitcnt vmcnt(5)
	ds_write_b128 v183, v[168:171] offset:27648
	s_waitcnt vmcnt(4)
	ds_write_b128 v183, v[172:175] offset:32256
	s_waitcnt vmcnt(3)
	ds_write_b128 v183, v[140:143] offset:36864
	s_waitcnt vmcnt(2)
	ds_write_b128 v183, v[136:139] offset:41472
	s_waitcnt vmcnt(1)
	ds_write_b128 v183, v[128:131] offset:46080
	s_waitcnt vmcnt(0)
	ds_write_b128 v183, v[132:135] offset:50688
	s_waitcnt lgkmcnt(0)
	s_barrier
	ds_read_b128 v[128:131], v182 offset:41472
	ds_read_b128 v[132:135], v182 offset:36864
	ds_read_b128 v[136:139], v182 offset:36896
	ds_read_b128 v[140:143], v179
	ds_read_b128 v[144:147], v179 offset:32
	s_waitcnt lgkmcnt(1)
	v_mfma_f32_32x32x16_bf16 v[112:127], v[140:143], v[132:135], v[112:127]
	v_readlane_b32 s16, v253, 32
	v_readlane_b32 s28, v253, 44
	v_readlane_b32 s29, v253, 45
	v_readlane_b32 s17, v253, 33
	v_readlane_b32 s18, v253, 34
	v_readlane_b32 s19, v253, 35
	v_readlane_b32 s20, v253, 36
	v_mfma_f32_32x32x16_bf16 v[96:111], v[140:143], v[128:131], v[96:111]
	ds_read_b128 v[140:143], v179 offset:4608
	v_readlane_b32 s21, v253, 37
	v_readlane_b32 s22, v253, 38
	v_readlane_b32 s23, v253, 39
	v_readlane_b32 s24, v253, 40
	v_readlane_b32 s25, v253, 41
	v_readlane_b32 s26, v253, 42
	s_waitcnt lgkmcnt(0)
	v_mfma_f32_32x32x16_bf16 v[80:95], v[140:143], v[132:135], v[80:95]
	v_readlane_b32 s27, v253, 43
	v_readlane_b32 s30, v253, 46
	v_readlane_b32 s31, v253, 47
	v_mfma_f32_32x32x16_bf16 v[64:79], v[140:143], v[128:131], v[64:79]
	ds_read_b128 v[140:143], v179 offset:9216
	s_waitcnt lgkmcnt(0)
	v_mfma_f32_32x32x16_bf16 v[48:63], v[140:143], v[132:135], v[48:63]
	v_mfma_f32_32x32x16_bf16 v[32:47], v[140:143], v[128:131], v[32:47]
	ds_read_b128 v[140:143], v177
	ds_read_b128 v[148:151], v177 offset:32
	s_waitcnt lgkmcnt(1)
	v_mfma_f32_32x32x16_bf16 v[16:31], v[140:143], v[132:135], v[16:31]
	ds_read_b128 v[132:135], v179 offset:4640
	v_mfma_f32_32x32x16_bf16 v[0:15], v[140:143], v[128:131], v[0:15]
	ds_read_b128 v[128:131], v182 offset:41504
	s_waitcnt lgkmcnt(1)
	v_mfma_f32_32x32x16_bf16 v[80:95], v[132:135], v[136:139], v[80:95]
	s_waitcnt lgkmcnt(0)
	v_mfma_f32_32x32x16_bf16 v[64:79], v[132:135], v[128:131], v[64:79]
	ds_read_b128 v[132:135], v179 offset:9248
	v_mfma_f32_32x32x16_bf16 v[112:127], v[144:147], v[136:139], v[112:127]
	v_mfma_f32_32x32x16_bf16 v[96:111], v[144:147], v[128:131], v[96:111]
	s_waitcnt lgkmcnt(0)
	v_mfma_f32_32x32x16_bf16 v[48:63], v[132:135], v[136:139], v[48:63]
	v_mfma_f32_32x32x16_bf16 v[32:47], v[132:135], v[128:131], v[32:47]
	v_mfma_f32_32x32x16_bf16 v[16:31], v[148:151], v[136:139], v[16:31]
	v_mfma_f32_32x32x16_bf16 v[0:15], v[148:151], v[128:131], v[0:15]
	ds_read_b128 v[128:131], v182 offset:36928
	ds_read_b128 v[132:135], v182 offset:41536
	ds_read_b128 v[136:139], v179 offset:64
	s_waitcnt lgkmcnt(0)
	v_mfma_f32_32x32x16_bf16 v[112:127], v[136:139], v[128:131], v[112:127]
	v_mfma_f32_32x32x16_bf16 v[96:111], v[136:139], v[132:135], v[96:111]
	ds_read_b128 v[136:139], v179 offset:4672
	s_waitcnt lgkmcnt(0)
	v_mfma_f32_32x32x16_bf16 v[80:95], v[136:139], v[128:131], v[80:95]
	v_mfma_f32_32x32x16_bf16 v[64:79], v[136:139], v[132:135], v[64:79]
	ds_read_b128 v[136:139], v179 offset:9280
	s_waitcnt lgkmcnt(0)
	v_mfma_f32_32x32x16_bf16 v[48:63], v[136:139], v[128:131], v[48:63]
	v_mfma_f32_32x32x16_bf16 v[32:47], v[136:139], v[132:135], v[32:47]
	ds_read_b128 v[136:139], v177 offset:64
	s_waitcnt lgkmcnt(0)
	v_mfma_f32_32x32x16_bf16 v[16:31], v[136:139], v[128:131], v[16:31]
	v_mfma_f32_32x32x16_bf16 v[0:15], v[136:139], v[132:135], v[0:15]
	ds_read_b128 v[128:131], v182 offset:36960
	ds_read_b128 v[132:135], v182 offset:41568
	ds_read_b128 v[136:139], v179 offset:96
	s_waitcnt lgkmcnt(0)
	v_mfma_f32_32x32x16_bf16 v[112:127], v[136:139], v[128:131], v[112:127]
	v_mfma_f32_32x32x16_bf16 v[96:111], v[136:139], v[132:135], v[96:111]
	ds_read_b128 v[136:139], v179 offset:4704
	s_waitcnt lgkmcnt(0)
	v_mfma_f32_32x32x16_bf16 v[80:95], v[136:139], v[128:131], v[80:95]
	v_mfma_f32_32x32x16_bf16 v[64:79], v[136:139], v[132:135], v[64:79]
	ds_read_b128 v[136:139], v179 offset:9312
	s_waitcnt lgkmcnt(0)
	v_mfma_f32_32x32x16_bf16 v[48:63], v[136:139], v[128:131], v[48:63]
	v_mfma_f32_32x32x16_bf16 v[32:47], v[136:139], v[132:135], v[32:47]
	ds_read_b128 v[136:139], v177 offset:96
	s_waitcnt lgkmcnt(0)
	s_barrier
; DI void phase_resid(const Params& p, const bfu* A, int lda, const bfu* Bt, int K, char* smem) {
;     ...
;     EPI_BEGINM(acc, 4)
;       float* xp = p.out + (size_t)row * 1024 + col;
;       float nv = *xp + v; *xp = nv; p.xb[(size_t)row * 1024 + col] = f2bf(nv);
;     EPI_END
	v_mfma_f32_32x32x16_bf16 v[16:31], v[136:139], v[128:131], v[16:31]
	v_mfma_f32_32x32x16_bf16 v[0:15], v[136:139], v[132:135], v[0:15]
	v_add_u32_e32 v176, s3, v180
	v_or_b32_e32 v177, s4, v181
	v_lshlrev_b32_e32 v176, 12, v176
	v_lshl_add_u32 v176, v177, 2, v176
	v_lshrrev_b32_e32 v177, 1, v176
	v_readlane_b32 s4, v254, 38
	v_readlane_b32 s5, v254, 39
	global_load_dword v128, v176, s[28:29]
	global_load_dword v129, v176, s[28:29] offset:128
	v_add_u32_e32 v178, 0x1000, v176
	global_load_dword v130, v178, s[28:29]
	global_load_dword v131, v178, s[28:29] offset:128
	v_add_u32_e32 v178, 0x2000, v176
	global_load_dword v132, v178, s[28:29]
	global_load_dword v133, v178, s[28:29] offset:128
	v_add_u32_e32 v178, 0x3000, v176
	global_load_dword v134, v178, s[28:29]
	global_load_dword v135, v178, s[28:29] offset:128
	v_add_u32_e32 v178, 0x8000, v176
	global_load_dword v136, v178, s[28:29]
	global_load_dword v137, v178, s[28:29] offset:128
	v_add_u32_e32 v178, 0x9000, v176
	global_load_dword v138, v178, s[28:29]
	global_load_dword v139, v178, s[28:29] offset:128
	v_add_u32_e32 v178, 0xa000, v176
	global_load_dword v140, v178, s[28:29]
	global_load_dword v141, v178, s[28:29] offset:128
	v_add_u32_e32 v178, 0xb000, v176
	global_load_dword v142, v178, s[28:29]
	global_load_dword v143, v178, s[28:29] offset:128
	v_add_u32_e32 v178, 0x10000, v176
	global_load_dword v144, v178, s[28:29]
	global_load_dword v145, v178, s[28:29] offset:128
	v_add_u32_e32 v178, 0x11000, v176
	global_load_dword v146, v178, s[28:29]
	global_load_dword v147, v178, s[28:29] offset:128
	v_add_u32_e32 v178, 0x12000, v176
	global_load_dword v148, v178, s[28:29]
	global_load_dword v149, v178, s[28:29] offset:128
	v_add_u32_e32 v178, 0x13000, v176
	global_load_dword v150, v178, s[28:29]
	global_load_dword v151, v178, s[28:29] offset:128
	v_add_u32_e32 v178, 0x18000, v176
	global_load_dword v152, v178, s[28:29]
	global_load_dword v153, v178, s[28:29] offset:128
	v_add_u32_e32 v178, 0x19000, v176
	global_load_dword v154, v178, s[28:29]
	global_load_dword v155, v178, s[28:29] offset:128
	v_add_u32_e32 v178, 0x1a000, v176
	global_load_dword v156, v178, s[28:29]
	global_load_dword v157, v178, s[28:29] offset:128
	v_add_u32_e32 v178, 0x1b000, v176
	global_load_dword v158, v178, s[28:29]
	global_load_dword v159, v178, s[28:29] offset:128
	v_add_u32_e32 v178, 0x20000, v176
	global_load_dword v160, v178, s[28:29]
	global_load_dword v161, v178, s[28:29] offset:128
	v_add_u32_e32 v178, 0x21000, v176
	global_load_dword v162, v178, s[28:29]
	global_load_dword v163, v178, s[28:29] offset:128
	v_add_u32_e32 v178, 0x22000, v176
	global_load_dword v164, v178, s[28:29]
	global_load_dword v165, v178, s[28:29] offset:128
	v_add_u32_e32 v178, 0x23000, v176
	global_load_dword v166, v178, s[28:29]
	global_load_dword v167, v178, s[28:29] offset:128
	v_add_u32_e32 v178, 0x28000, v176
	global_load_dword v168, v178, s[28:29]
	global_load_dword v169, v178, s[28:29] offset:128
	v_add_u32_e32 v178, 0x29000, v176
	global_load_dword v170, v178, s[28:29]
	global_load_dword v171, v178, s[28:29] offset:128
	v_add_u32_e32 v178, 0x2a000, v176
	global_load_dword v172, v178, s[28:29]
	global_load_dword v173, v178, s[28:29] offset:128
	v_add_u32_e32 v178, 0x2b000, v176
	global_load_dword v174, v178, s[28:29]
	global_load_dword v175, v178, s[28:29] offset:128
	v_add_u32_e32 v178, 0x30000, v176
	global_load_dword v184, v178, s[28:29]
	global_load_dword v185, v178, s[28:29] offset:128
	v_add_u32_e32 v178, 0x31000, v176
	global_load_dword v186, v178, s[28:29]
	global_load_dword v187, v178, s[28:29] offset:128
	v_add_u32_e32 v178, 0x32000, v176
	global_load_dword v190, v178, s[28:29]
	global_load_dword v191, v178, s[28:29] offset:128
	v_add_u32_e32 v178, 0x33000, v176
	global_load_dword v192, v178, s[28:29]
	global_load_dword v193, v178, s[28:29] offset:128
	v_add_u32_e32 v178, 0x38000, v176
	global_load_dword v194, v178, s[28:29]
	global_load_dword v195, v178, s[28:29] offset:128
	v_add_u32_e32 v178, 0x39000, v176
	global_load_dword v196, v178, s[28:29]
	global_load_dword v197, v178, s[28:29] offset:128
	v_add_u32_e32 v178, 0x3a000, v176
	global_load_dword v198, v178, s[28:29]
	global_load_dword v199, v178, s[28:29] offset:128
	v_add_u32_e32 v178, 0x3b000, v176
	global_load_dword v200, v178, s[28:29]
	global_load_dword v201, v178, s[28:29] offset:128
	s_waitcnt vmcnt(32)
; DI void phase_resid(const Params& p, const bfu* A, int lda, const bfu* Bt, int K, char* smem) {
;     ...
;     EPI_BEGINM(acc, 4)
;       float* xp = p.out + (size_t)row * 1024 + col;
;       float nv = *xp + v; *xp = nv; p.xb[(size_t)row * 1024 + col] = f2bf(nv);
;     EPI_END
	v_add_f32_e32 v112, v112, v128
	global_store_dword v176, v112, s[28:29]
	v_cvt_pk_bf16_f32 v128, v112, v112
	global_store_short v177, v128, s[36:37]
	v_add_f32_e32 v96, v96, v129
	global_store_dword v176, v96, s[28:29] offset:128
	v_cvt_pk_bf16_f32 v129, v96, v96
	global_store_short v177, v129, s[36:37] offset:64
	v_add_u32_e32 v178, 0x1000, v176
	v_add_u32_e32 v179, 0x800, v177
	v_add_f32_e32 v113, v113, v130
	global_store_dword v178, v113, s[28:29]
	v_cvt_pk_bf16_f32 v130, v113, v113
	global_store_short v179, v130, s[36:37]
	v_add_f32_e32 v97, v97, v131
	global_store_dword v178, v97, s[28:29] offset:128
	v_cvt_pk_bf16_f32 v131, v97, v97
	global_store_short v179, v131, s[36:37] offset:64
	v_add_u32_e32 v178, 0x2000, v176
	v_add_u32_e32 v179, 0x1000, v177
	v_add_f32_e32 v114, v114, v132
	global_store_dword v178, v114, s[28:29]
	v_cvt_pk_bf16_f32 v132, v114, v114
	global_store_short v179, v132, s[36:37]
	v_add_f32_e32 v98, v98, v133
	global_store_dword v178, v98, s[28:29] offset:128
	v_cvt_pk_bf16_f32 v133, v98, v98
	global_store_short v179, v133, s[36:37] offset:64
	v_add_u32_e32 v178, 0x3000, v176
	v_add_u32_e32 v179, 0x1800, v177
	v_add_f32_e32 v115, v115, v134
	global_store_dword v178, v115, s[28:29]
	v_cvt_pk_bf16_f32 v134, v115, v115
	global_store_short v179, v134, s[36:37]
	v_add_f32_e32 v99, v99, v135
	global_store_dword v178, v99, s[28:29] offset:128
	v_cvt_pk_bf16_f32 v135, v99, v99
	global_store_short v179, v135, s[36:37] offset:64
	v_add_u32_e32 v178, 0x8000, v176
	v_add_u32_e32 v179, 0x4000, v177
	v_add_f32_e32 v116, v116, v136
	global_store_dword v178, v116, s[28:29]
	v_cvt_pk_bf16_f32 v136, v116, v116
	global_store_short v179, v136, s[36:37]
	v_add_f32_e32 v100, v100, v137
	global_store_dword v178, v100, s[28:29] offset:128
	v_cvt_pk_bf16_f32 v137, v100, v100
	global_store_short v179, v137, s[36:37] offset:64
	v_add_u32_e32 v178, 0x9000, v176
	v_add_u32_e32 v179, 0x4800, v177
	v_add_f32_e32 v117, v117, v138
	global_store_dword v178, v117, s[28:29]
	v_cvt_pk_bf16_f32 v138, v117, v117
	global_store_short v179, v138, s[36:37]
	v_add_f32_e32 v101, v101, v139
	global_store_dword v178, v101, s[28:29] offset:128
	v_cvt_pk_bf16_f32 v139, v101, v101
	global_store_short v179, v139, s[36:37] offset:64
	v_add_u32_e32 v178, 0xa000, v176
	v_add_u32_e32 v179, 0x5000, v177
	v_add_f32_e32 v118, v118, v140
	global_store_dword v178, v118, s[28:29]
	v_cvt_pk_bf16_f32 v140, v118, v118
	global_store_short v179, v140, s[36:37]
	v_add_f32_e32 v102, v102, v141
	global_store_dword v178, v102, s[28:29] offset:128
	v_cvt_pk_bf16_f32 v141, v102, v102
	global_store_short v179, v141, s[36:37] offset:64
	v_add_u32_e32 v178, 0xb000, v176
	v_add_u32_e32 v179, 0x5800, v177
	v_add_f32_e32 v119, v119, v142
	global_store_dword v178, v119, s[28:29]
	v_cvt_pk_bf16_f32 v142, v119, v119
	global_store_short v179, v142, s[36:37]
	v_add_f32_e32 v103, v103, v143
	global_store_dword v178, v103, s[28:29] offset:128
	v_cvt_pk_bf16_f32 v143, v103, v103
	global_store_short v179, v143, s[36:37] offset:64
	v_add_u32_e32 v178, 0x10000, v176
	v_add_u32_e32 v179, 0x8000, v177
	v_add_f32_e32 v120, v120, v144
	global_store_dword v178, v120, s[28:29]
	v_cvt_pk_bf16_f32 v144, v120, v120
	global_store_short v179, v144, s[36:37]
	v_add_f32_e32 v104, v104, v145
	global_store_dword v178, v104, s[28:29] offset:128
	v_cvt_pk_bf16_f32 v145, v104, v104
	global_store_short v179, v145, s[36:37] offset:64
	v_add_u32_e32 v178, 0x11000, v176
	v_add_u32_e32 v179, 0x8800, v177
	v_add_f32_e32 v121, v121, v146
	global_store_dword v178, v121, s[28:29]
	v_cvt_pk_bf16_f32 v146, v121, v121
	global_store_short v179, v146, s[36:37]
	v_add_f32_e32 v105, v105, v147
	global_store_dword v178, v105, s[28:29] offset:128
	v_cvt_pk_bf16_f32 v147, v105, v105
	global_store_short v179, v147, s[36:37] offset:64
	v_add_u32_e32 v178, 0x12000, v176
	v_add_u32_e32 v179, 0x9000, v177
	v_add_f32_e32 v122, v122, v148
	global_store_dword v178, v122, s[28:29]
	v_cvt_pk_bf16_f32 v148, v122, v122
	global_store_short v179, v148, s[36:37]
	v_add_f32_e32 v106, v106, v149
	global_store_dword v178, v106, s[28:29] offset:128
	v_cvt_pk_bf16_f32 v149, v106, v106
	global_store_short v179, v149, s[36:37] offset:64
	v_add_u32_e32 v178, 0x13000, v176
	v_add_u32_e32 v179, 0x9800, v177
	v_add_f32_e32 v123, v123, v150
	global_store_dword v178, v123, s[28:29]
	v_cvt_pk_bf16_f32 v150, v123, v123
	global_store_short v179, v150, s[36:37]
	v_add_f32_e32 v107, v107, v151
	global_store_dword v178, v107, s[28:29] offset:128
	v_cvt_pk_bf16_f32 v151, v107, v107
	global_store_short v179, v151, s[36:37] offset:64
	v_add_u32_e32 v178, 0x18000, v176
	v_add_u32_e32 v179, 0xc000, v177
	v_add_f32_e32 v124, v124, v152
	global_store_dword v178, v124, s[28:29]
	v_cvt_pk_bf16_f32 v152, v124, v124
	global_store_short v179, v152, s[36:37]
	v_add_f32_e32 v108, v108, v153
	global_store_dword v178, v108, s[28:29] offset:128
	v_cvt_pk_bf16_f32 v153, v108, v108
	global_store_short v179, v153, s[36:37] offset:64
	v_add_u32_e32 v178, 0x19000, v176
	v_add_u32_e32 v179, 0xc800, v177
	v_add_f32_e32 v125, v125, v154
	global_store_dword v178, v125, s[28:29]
	v_cvt_pk_bf16_f32 v154, v125, v125
	global_store_short v179, v154, s[36:37]
	v_add_f32_e32 v109, v109, v155
	global_store_dword v178, v109, s[28:29] offset:128
	v_cvt_pk_bf16_f32 v155, v109, v109
	global_store_short v179, v155, s[36:37] offset:64
	v_add_u32_e32 v178, 0x1a000, v176
	v_add_u32_e32 v179, 0xd000, v177
	v_add_f32_e32 v126, v126, v156
	global_store_dword v178, v126, s[28:29]
	v_cvt_pk_bf16_f32 v156, v126, v126
	global_store_short v179, v156, s[36:37]
	v_add_f32_e32 v110, v110, v157
; DI void phase_resid(const Params& p, const bfu* A, int lda, const bfu* Bt, int K, char* smem) {
;     ...
;     EPI_BEGINM(acc, 4)
;       float* xp = p.out + (size_t)row * 1024 + col;
;       float nv = *xp + v; *xp = nv; p.xb[(size_t)row * 1024 + col] = f2bf(nv);
;     EPI_END
	global_store_dword v178, v110, s[28:29] offset:128
	v_cvt_pk_bf16_f32 v157, v110, v110
	global_store_short v179, v157, s[36:37] offset:64
	v_add_u32_e32 v178, 0x1b000, v176
	v_add_u32_e32 v179, 0xd800, v177
	v_add_f32_e32 v127, v127, v158
	global_store_dword v178, v127, s[28:29]
	v_cvt_pk_bf16_f32 v158, v127, v127
	global_store_short v179, v158, s[36:37]
	v_add_f32_e32 v111, v111, v159
	global_store_dword v178, v111, s[28:29] offset:128
	v_cvt_pk_bf16_f32 v159, v111, v111
	global_store_short v179, v159, s[36:37] offset:64
	v_add_u32_e32 v178, 0x40000, v176
	global_load_dword v128, v178, s[28:29]
	global_load_dword v129, v178, s[28:29] offset:128
	v_add_u32_e32 v178, 0x41000, v176
	global_load_dword v130, v178, s[28:29]
	global_load_dword v131, v178, s[28:29] offset:128
	v_add_u32_e32 v178, 0x42000, v176
	global_load_dword v132, v178, s[28:29]
	global_load_dword v133, v178, s[28:29] offset:128
	v_add_u32_e32 v178, 0x43000, v176
	global_load_dword v134, v178, s[28:29]
	global_load_dword v135, v178, s[28:29] offset:128
	v_add_u32_e32 v178, 0x48000, v176
	global_load_dword v136, v178, s[28:29]
	global_load_dword v137, v178, s[28:29] offset:128
	v_add_u32_e32 v178, 0x49000, v176
	global_load_dword v138, v178, s[28:29]
	global_load_dword v139, v178, s[28:29] offset:128
	v_add_u32_e32 v178, 0x4a000, v176
	global_load_dword v140, v178, s[28:29]
	global_load_dword v141, v178, s[28:29] offset:128
	v_add_u32_e32 v178, 0x4b000, v176
	global_load_dword v142, v178, s[28:29]
	global_load_dword v143, v178, s[28:29] offset:128
	v_add_u32_e32 v178, 0x50000, v176
	global_load_dword v144, v178, s[28:29]
	global_load_dword v145, v178, s[28:29] offset:128
	v_add_u32_e32 v178, 0x51000, v176
	global_load_dword v146, v178, s[28:29]
	global_load_dword v147, v178, s[28:29] offset:128
	v_add_u32_e32 v178, 0x52000, v176
	global_load_dword v148, v178, s[28:29]
	global_load_dword v149, v178, s[28:29] offset:128
	v_add_u32_e32 v178, 0x53000, v176
	global_load_dword v150, v178, s[28:29]
	global_load_dword v151, v178, s[28:29] offset:128
	v_add_u32_e32 v178, 0x58000, v176
	global_load_dword v152, v178, s[28:29]
	global_load_dword v153, v178, s[28:29] offset:128
	v_add_u32_e32 v178, 0x59000, v176
	global_load_dword v154, v178, s[28:29]
	global_load_dword v155, v178, s[28:29] offset:128
	v_add_u32_e32 v178, 0x5a000, v176
	global_load_dword v156, v178, s[28:29]
	global_load_dword v157, v178, s[28:29] offset:128
	v_add_u32_e32 v178, 0x5b000, v176
	global_load_dword v158, v178, s[28:29]
	global_load_dword v159, v178, s[28:29] offset:128
	s_waitcnt vmcnt(63)
	v_add_u32_e32 v178, 0x20000, v176
	v_add_u32_e32 v179, 0x10000, v177
	v_add_f32_e32 v80, v80, v160
	global_store_dword v178, v80, s[28:29]
	v_cvt_pk_bf16_f32 v160, v80, v80
	global_store_short v179, v160, s[36:37]
	v_add_f32_e32 v64, v64, v161
	global_store_dword v178, v64, s[28:29] offset:128
	v_cvt_pk_bf16_f32 v161, v64, v64
	global_store_short v179, v161, s[36:37] offset:64
	v_add_u32_e32 v178, 0x21000, v176
	v_add_u32_e32 v179, 0x10800, v177
	v_add_f32_e32 v81, v81, v162
	global_store_dword v178, v81, s[28:29]
	v_cvt_pk_bf16_f32 v162, v81, v81
	global_store_short v179, v162, s[36:37]
	v_add_f32_e32 v65, v65, v163
	global_store_dword v178, v65, s[28:29] offset:128
	v_cvt_pk_bf16_f32 v163, v65, v65
	global_store_short v179, v163, s[36:37] offset:64
	v_add_u32_e32 v178, 0x22000, v176
	v_add_u32_e32 v179, 0x11000, v177
	v_add_f32_e32 v82, v82, v164
	global_store_dword v178, v82, s[28:29]
	v_cvt_pk_bf16_f32 v164, v82, v82
	global_store_short v179, v164, s[36:37]
	v_add_f32_e32 v66, v66, v165
	global_store_dword v178, v66, s[28:29] offset:128
	v_cvt_pk_bf16_f32 v165, v66, v66
	global_store_short v179, v165, s[36:37] offset:64
	v_add_u32_e32 v178, 0x23000, v176
	v_add_u32_e32 v179, 0x11800, v177
	v_add_f32_e32 v83, v83, v166
	global_store_dword v178, v83, s[28:29]
	v_cvt_pk_bf16_f32 v166, v83, v83
	global_store_short v179, v166, s[36:37]
	v_add_f32_e32 v67, v67, v167
	global_store_dword v178, v67, s[28:29] offset:128
	v_cvt_pk_bf16_f32 v167, v67, v67
	global_store_short v179, v167, s[36:37] offset:64
	v_add_u32_e32 v178, 0x28000, v176
	v_add_u32_e32 v179, 0x14000, v177
	v_add_f32_e32 v84, v84, v168
	global_store_dword v178, v84, s[28:29]
	v_cvt_pk_bf16_f32 v168, v84, v84
	global_store_short v179, v168, s[36:37]
	v_add_f32_e32 v68, v68, v169
	global_store_dword v178, v68, s[28:29] offset:128
	v_cvt_pk_bf16_f32 v169, v68, v68
	global_store_short v179, v169, s[36:37] offset:64
	v_add_u32_e32 v178, 0x29000, v176
	v_add_u32_e32 v179, 0x14800, v177
	v_add_f32_e32 v85, v85, v170
	global_store_dword v178, v85, s[28:29]
	v_cvt_pk_bf16_f32 v170, v85, v85
	global_store_short v179, v170, s[36:37]
	v_add_f32_e32 v69, v69, v171
	global_store_dword v178, v69, s[28:29] offset:128
	v_cvt_pk_bf16_f32 v171, v69, v69
	global_store_short v179, v171, s[36:37] offset:64
	v_add_u32_e32 v178, 0x2a000, v176
	v_add_u32_e32 v179, 0x15000, v177
	v_add_f32_e32 v86, v86, v172
	global_store_dword v178, v86, s[28:29]
	v_cvt_pk_bf16_f32 v172, v86, v86
	global_store_short v179, v172, s[36:37]
	v_add_f32_e32 v70, v70, v173
	global_store_dword v178, v70, s[28:29] offset:128
	v_cvt_pk_bf16_f32 v173, v70, v70
	global_store_short v179, v173, s[36:37] offset:64
	v_add_u32_e32 v178, 0x2b000, v176
	v_add_u32_e32 v179, 0x15800, v177
	v_add_f32_e32 v87, v87, v174
	global_store_dword v178, v87, s[28:29]
	v_cvt_pk_bf16_f32 v174, v87, v87
	global_store_short v179, v174, s[36:37]
	v_add_f32_e32 v71, v71, v175
	global_store_dword v178, v71, s[28:29] offset:128
	v_cvt_pk_bf16_f32 v175, v71, v71
	global_store_short v179, v175, s[36:37] offset:64
	v_add_u32_e32 v178, 0x30000, v176
; DI void phase_resid(const Params& p, const bfu* A, int lda, const bfu* Bt, int K, char* smem) {
;     ...
;     EPI_BEGINM(acc, 4)
;       float* xp = p.out + (size_t)row * 1024 + col;
;       float nv = *xp + v; *xp = nv; p.xb[(size_t)row * 1024 + col] = f2bf(nv);
;     EPI_END
	v_add_u32_e32 v179, 0x18000, v177
	v_add_f32_e32 v88, v88, v184
	global_store_dword v178, v88, s[28:29]
	v_cvt_pk_bf16_f32 v184, v88, v88
	global_store_short v179, v184, s[36:37]
	v_add_f32_e32 v72, v72, v185
	global_store_dword v178, v72, s[28:29] offset:128
	v_cvt_pk_bf16_f32 v185, v72, v72
	global_store_short v179, v185, s[36:37] offset:64
	v_add_u32_e32 v178, 0x31000, v176
	v_add_u32_e32 v179, 0x18800, v177
	v_add_f32_e32 v89, v89, v186
	global_store_dword v178, v89, s[28:29]
	v_cvt_pk_bf16_f32 v186, v89, v89
	global_store_short v179, v186, s[36:37]
	v_add_f32_e32 v73, v73, v187
	global_store_dword v178, v73, s[28:29] offset:128
	v_cvt_pk_bf16_f32 v187, v73, v73
	global_store_short v179, v187, s[36:37] offset:64
	v_add_u32_e32 v178, 0x32000, v176
	v_add_u32_e32 v179, 0x19000, v177
	v_add_f32_e32 v90, v90, v190
	global_store_dword v178, v90, s[28:29]
	v_cvt_pk_bf16_f32 v190, v90, v90
	global_store_short v179, v190, s[36:37]
	v_add_f32_e32 v74, v74, v191
	global_store_dword v178, v74, s[28:29] offset:128
	v_cvt_pk_bf16_f32 v191, v74, v74
	global_store_short v179, v191, s[36:37] offset:64
	v_add_u32_e32 v178, 0x33000, v176
	v_add_u32_e32 v179, 0x19800, v177
	v_add_f32_e32 v91, v91, v192
	global_store_dword v178, v91, s[28:29]
	v_cvt_pk_bf16_f32 v192, v91, v91
	global_store_short v179, v192, s[36:37]
	v_add_f32_e32 v75, v75, v193
	global_store_dword v178, v75, s[28:29] offset:128
	v_cvt_pk_bf16_f32 v193, v75, v75
	global_store_short v179, v193, s[36:37] offset:64
	v_add_u32_e32 v178, 0x38000, v176
	v_add_u32_e32 v179, 0x1c000, v177
	v_add_f32_e32 v92, v92, v194
	global_store_dword v178, v92, s[28:29]
	v_cvt_pk_bf16_f32 v194, v92, v92
	global_store_short v179, v194, s[36:37]
	v_add_f32_e32 v76, v76, v195
	global_store_dword v178, v76, s[28:29] offset:128
	v_cvt_pk_bf16_f32 v195, v76, v76
	global_store_short v179, v195, s[36:37] offset:64
	v_add_u32_e32 v178, 0x39000, v176
	v_add_u32_e32 v179, 0x1c800, v177
	v_add_f32_e32 v93, v93, v196
	global_store_dword v178, v93, s[28:29]
	v_cvt_pk_bf16_f32 v196, v93, v93
	global_store_short v179, v196, s[36:37]
	v_add_f32_e32 v77, v77, v197
	global_store_dword v178, v77, s[28:29] offset:128
	v_cvt_pk_bf16_f32 v197, v77, v77
	global_store_short v179, v197, s[36:37] offset:64
	v_add_u32_e32 v178, 0x3a000, v176
	v_add_u32_e32 v179, 0x1d000, v177
	v_add_f32_e32 v94, v94, v198
	global_store_dword v178, v94, s[28:29]
	v_cvt_pk_bf16_f32 v198, v94, v94
	global_store_short v179, v198, s[36:37]
	v_add_f32_e32 v78, v78, v199
	global_store_dword v178, v78, s[28:29] offset:128
	v_cvt_pk_bf16_f32 v199, v78, v78
	global_store_short v179, v199, s[36:37] offset:64
	v_add_u32_e32 v178, 0x3b000, v176
	v_add_u32_e32 v179, 0x1d800, v177
	v_add_f32_e32 v95, v95, v200
	global_store_dword v178, v95, s[28:29]
	v_cvt_pk_bf16_f32 v200, v95, v95
	global_store_short v179, v200, s[36:37]
	v_add_f32_e32 v79, v79, v201
	global_store_dword v178, v79, s[28:29] offset:128
	v_cvt_pk_bf16_f32 v201, v79, v79
	global_store_short v179, v201, s[36:37] offset:64
	v_add_u32_e32 v178, 0x60000, v176
	global_load_dword v160, v178, s[28:29]
	global_load_dword v161, v178, s[28:29] offset:128
	v_add_u32_e32 v178, 0x61000, v176
	global_load_dword v162, v178, s[28:29]
	global_load_dword v163, v178, s[28:29] offset:128
	v_add_u32_e32 v178, 0x62000, v176
	global_load_dword v164, v178, s[28:29]
	global_load_dword v165, v178, s[28:29] offset:128
	v_add_u32_e32 v178, 0x63000, v176
	global_load_dword v166, v178, s[28:29]
	global_load_dword v167, v178, s[28:29] offset:128
	v_add_u32_e32 v178, 0x68000, v176
	global_load_dword v168, v178, s[28:29]
	global_load_dword v169, v178, s[28:29] offset:128
	v_add_u32_e32 v178, 0x69000, v176
	global_load_dword v170, v178, s[28:29]
	global_load_dword v171, v178, s[28:29] offset:128
	v_add_u32_e32 v178, 0x6a000, v176
	global_load_dword v172, v178, s[28:29]
	global_load_dword v173, v178, s[28:29] offset:128
	v_add_u32_e32 v178, 0x6b000, v176
	global_load_dword v174, v178, s[28:29]
	global_load_dword v175, v178, s[28:29] offset:128
	v_add_u32_e32 v178, 0x70000, v176
	global_load_dword v184, v178, s[28:29]
	global_load_dword v185, v178, s[28:29] offset:128
	v_add_u32_e32 v178, 0x71000, v176
	global_load_dword v186, v178, s[28:29]
	global_load_dword v187, v178, s[28:29] offset:128
	v_add_u32_e32 v178, 0x72000, v176
	global_load_dword v190, v178, s[28:29]
	global_load_dword v191, v178, s[28:29] offset:128
	v_add_u32_e32 v178, 0x73000, v176
	global_load_dword v192, v178, s[28:29]
	global_load_dword v193, v178, s[28:29] offset:128
	v_add_u32_e32 v178, 0x78000, v176
	global_load_dword v194, v178, s[28:29]
	global_load_dword v195, v178, s[28:29] offset:128
	v_add_u32_e32 v178, 0x79000, v176
	global_load_dword v196, v178, s[28:29]
	global_load_dword v197, v178, s[28:29] offset:128
	v_add_u32_e32 v178, 0x7a000, v176
	global_load_dword v198, v178, s[28:29]
	global_load_dword v199, v178, s[28:29] offset:128
	v_add_u32_e32 v178, 0x7b000, v176
	global_load_dword v200, v178, s[28:29]
	global_load_dword v201, v178, s[28:29] offset:128
	s_waitcnt vmcnt(63)
; DI void phase_resid(const Params& p, const bfu* A, int lda, const bfu* Bt, int K, char* smem) {
;     ...
;     EPI_BEGINM(acc, 4)
;       float* xp = p.out + (size_t)row * 1024 + col;
;       float nv = *xp + v; *xp = nv; p.xb[(size_t)row * 1024 + col] = f2bf(nv);
;     EPI_END
	v_add_u32_e32 v178, 0x40000, v176
	v_add_u32_e32 v179, 0x20000, v177
	v_add_f32_e32 v48, v48, v128
	global_store_dword v178, v48, s[28:29]
	v_cvt_pk_bf16_f32 v128, v48, v48
	global_store_short v179, v128, s[36:37]
	v_add_f32_e32 v32, v32, v129
	global_store_dword v178, v32, s[28:29] offset:128
	v_cvt_pk_bf16_f32 v129, v32, v32
	global_store_short v179, v129, s[36:37] offset:64
	v_add_u32_e32 v178, 0x41000, v176
	v_add_u32_e32 v179, 0x20800, v177
	v_add_f32_e32 v49, v49, v130
	global_store_dword v178, v49, s[28:29]
	v_cvt_pk_bf16_f32 v130, v49, v49
	global_store_short v179, v130, s[36:37]
	v_add_f32_e32 v33, v33, v131
	global_store_dword v178, v33, s[28:29] offset:128
	v_cvt_pk_bf16_f32 v131, v33, v33
	global_store_short v179, v131, s[36:37] offset:64
	v_add_u32_e32 v178, 0x42000, v176
	v_add_u32_e32 v179, 0x21000, v177
	v_add_f32_e32 v50, v50, v132
	global_store_dword v178, v50, s[28:29]
	v_cvt_pk_bf16_f32 v132, v50, v50
	global_store_short v179, v132, s[36:37]
	v_add_f32_e32 v34, v34, v133
	global_store_dword v178, v34, s[28:29] offset:128
	v_cvt_pk_bf16_f32 v133, v34, v34
	global_store_short v179, v133, s[36:37] offset:64
	v_add_u32_e32 v178, 0x43000, v176
	v_add_u32_e32 v179, 0x21800, v177
	v_add_f32_e32 v51, v51, v134
	global_store_dword v178, v51, s[28:29]
	v_cvt_pk_bf16_f32 v134, v51, v51
	global_store_short v179, v134, s[36:37]
	v_add_f32_e32 v35, v35, v135
	global_store_dword v178, v35, s[28:29] offset:128
	v_cvt_pk_bf16_f32 v135, v35, v35
	global_store_short v179, v135, s[36:37] offset:64
	v_add_u32_e32 v178, 0x48000, v176
	v_add_u32_e32 v179, 0x24000, v177
	v_add_f32_e32 v52, v52, v136
	global_store_dword v178, v52, s[28:29]
	v_cvt_pk_bf16_f32 v136, v52, v52
	global_store_short v179, v136, s[36:37]
	v_add_f32_e32 v36, v36, v137
	global_store_dword v178, v36, s[28:29] offset:128
	v_cvt_pk_bf16_f32 v137, v36, v36
	global_store_short v179, v137, s[36:37] offset:64
	v_add_u32_e32 v178, 0x49000, v176
	v_add_u32_e32 v179, 0x24800, v177
	v_add_f32_e32 v53, v53, v138
	global_store_dword v178, v53, s[28:29]
	v_cvt_pk_bf16_f32 v138, v53, v53
	global_store_short v179, v138, s[36:37]
	v_add_f32_e32 v37, v37, v139
	global_store_dword v178, v37, s[28:29] offset:128
	v_cvt_pk_bf16_f32 v139, v37, v37
	global_store_short v179, v139, s[36:37] offset:64
	v_add_u32_e32 v178, 0x4a000, v176
	v_add_u32_e32 v179, 0x25000, v177
	v_add_f32_e32 v54, v54, v140
	global_store_dword v178, v54, s[28:29]
	v_cvt_pk_bf16_f32 v140, v54, v54
	global_store_short v179, v140, s[36:37]
	v_add_f32_e32 v38, v38, v141
	global_store_dword v178, v38, s[28:29] offset:128
	v_cvt_pk_bf16_f32 v141, v38, v38
	global_store_short v179, v141, s[36:37] offset:64
	v_add_u32_e32 v178, 0x4b000, v176
	v_add_u32_e32 v179, 0x25800, v177
	v_add_f32_e32 v55, v55, v142
	global_store_dword v178, v55, s[28:29]
	v_cvt_pk_bf16_f32 v142, v55, v55
	global_store_short v179, v142, s[36:37]
	v_add_f32_e32 v39, v39, v143
	global_store_dword v178, v39, s[28:29] offset:128
	v_cvt_pk_bf16_f32 v143, v39, v39
	global_store_short v179, v143, s[36:37] offset:64
	v_add_u32_e32 v178, 0x50000, v176
	v_add_u32_e32 v179, 0x28000, v177
	v_add_f32_e32 v56, v56, v144
	global_store_dword v178, v56, s[28:29]
	v_cvt_pk_bf16_f32 v144, v56, v56
	global_store_short v179, v144, s[36:37]
	v_add_f32_e32 v40, v40, v145
	global_store_dword v178, v40, s[28:29] offset:128
	v_cvt_pk_bf16_f32 v145, v40, v40
	global_store_short v179, v145, s[36:37] offset:64
	v_add_u32_e32 v178, 0x51000, v176
	v_add_u32_e32 v179, 0x28800, v177
	v_add_f32_e32 v57, v57, v146
	global_store_dword v178, v57, s[28:29]
	v_cvt_pk_bf16_f32 v146, v57, v57
	global_store_short v179, v146, s[36:37]
	v_add_f32_e32 v41, v41, v147
	global_store_dword v178, v41, s[28:29] offset:128
	v_cvt_pk_bf16_f32 v147, v41, v41
	global_store_short v179, v147, s[36:37] offset:64
	v_add_u32_e32 v178, 0x52000, v176
	v_add_u32_e32 v179, 0x29000, v177
	v_add_f32_e32 v58, v58, v148
	global_store_dword v178, v58, s[28:29]
	v_cvt_pk_bf16_f32 v148, v58, v58
	global_store_short v179, v148, s[36:37]
	v_add_f32_e32 v42, v42, v149
	global_store_dword v178, v42, s[28:29] offset:128
	v_cvt_pk_bf16_f32 v149, v42, v42
	global_store_short v179, v149, s[36:37] offset:64
	v_add_u32_e32 v178, 0x53000, v176
	v_add_u32_e32 v179, 0x29800, v177
	v_add_f32_e32 v59, v59, v150
	global_store_dword v178, v59, s[28:29]
	v_cvt_pk_bf16_f32 v150, v59, v59
	global_store_short v179, v150, s[36:37]
	v_add_f32_e32 v43, v43, v151
	global_store_dword v178, v43, s[28:29] offset:128
	v_cvt_pk_bf16_f32 v151, v43, v43
	global_store_short v179, v151, s[36:37] offset:64
	v_add_u32_e32 v178, 0x58000, v176
	v_add_u32_e32 v179, 0x2c000, v177
	v_add_f32_e32 v60, v60, v152
	global_store_dword v178, v60, s[28:29]
	v_cvt_pk_bf16_f32 v152, v60, v60
	global_store_short v179, v152, s[36:37]
	v_add_f32_e32 v44, v44, v153
	global_store_dword v178, v44, s[28:29] offset:128
	v_cvt_pk_bf16_f32 v153, v44, v44
	global_store_short v179, v153, s[36:37] offset:64
	v_add_u32_e32 v178, 0x59000, v176
	v_add_u32_e32 v179, 0x2c800, v177
	v_add_f32_e32 v61, v61, v154
	global_store_dword v178, v61, s[28:29]
	v_cvt_pk_bf16_f32 v154, v61, v61
	global_store_short v179, v154, s[36:37]
	v_add_f32_e32 v45, v45, v155
	global_store_dword v178, v45, s[28:29] offset:128
	v_cvt_pk_bf16_f32 v155, v45, v45
	global_store_short v179, v155, s[36:37] offset:64
	v_add_u32_e32 v178, 0x5a000, v176
	v_add_u32_e32 v179, 0x2d000, v177
	v_add_f32_e32 v62, v62, v156
	global_store_dword v178, v62, s[28:29]
	v_cvt_pk_bf16_f32 v156, v62, v62
	global_store_short v179, v156, s[36:37]
	v_add_f32_e32 v46, v46, v157
	global_store_dword v178, v46, s[28:29] offset:128
	v_cvt_pk_bf16_f32 v157, v46, v46
	global_store_short v179, v157, s[36:37] offset:64
	v_add_u32_e32 v178, 0x5b000, v176
	v_add_u32_e32 v179, 0x2d800, v177
	v_add_f32_e32 v63, v63, v158
	global_store_dword v178, v63, s[28:29]
	v_cvt_pk_bf16_f32 v158, v63, v63
	global_store_short v179, v158, s[36:37]
	v_add_f32_e32 v47, v47, v159
	global_store_dword v178, v47, s[28:29] offset:128
	v_cvt_pk_bf16_f32 v159, v47, v47
	global_store_short v179, v159, s[36:37] offset:64
	s_waitcnt vmcnt(63)
; #define ZERO_ACCM(a, MT) _Pragma("unroll") for (int _m = 0; _m < MT; ++_m) _Pragma("unroll") for (int _n = 0; _n < 2; ++_n) _Pragma("unroll") for (int _i = 0; _i < 16; ++_i) a[_m][_n][_i] = 0.f;
; DI void phase_resid(const Params& p, const bfu* A, int lda, const bfu* Bt, int K, char* smem) {
;     ...
;   for (int id = blockIdx.x; id < 64 * 8; id += gridDim.x) {
;     int tm, tn; map_tile(id, 8, tm, tn);
;     const int m0 = tm * 256, n0 = tn * 128;
;     f32x16 acc[4][2]; ZERO_ACCM(acc, 4)
;     gemm_core<false, false, 4>(A, lda, Bt, K, K, m0, n0, acc, smem);
;     EPI_BEGINM(acc, 4)
;       float* xp = p.out + (size_t)row * 1024 + col;
;       float nv = *xp + v; *xp = nv; p.xb[(size_t)row * 1024 + col] = f2bf(nv);
;     EPI_END
	v_add_u32_e32 v178, 0x60000, v176
	v_add_u32_e32 v179, 0x30000, v177
	v_add_f32_e32 v16, v16, v160
	global_store_dword v178, v16, s[28:29]
	v_cvt_pk_bf16_f32 v160, v16, v16
	global_store_short v179, v160, s[36:37]
	v_add_f32_e32 v0, v0, v161
	global_store_dword v178, v0, s[28:29] offset:128
	v_cvt_pk_bf16_f32 v161, v0, v0
	global_store_short v179, v161, s[36:37] offset:64
	v_add_u32_e32 v178, 0x61000, v176
	v_add_u32_e32 v179, 0x30800, v177
	v_add_f32_e32 v17, v17, v162
	global_store_dword v178, v17, s[28:29]
	v_cvt_pk_bf16_f32 v162, v17, v17
	global_store_short v179, v162, s[36:37]
	v_add_f32_e32 v1, v1, v163
	global_store_dword v178, v1, s[28:29] offset:128
	v_cvt_pk_bf16_f32 v163, v1, v1
	global_store_short v179, v163, s[36:37] offset:64
	v_add_u32_e32 v178, 0x62000, v176
	v_add_u32_e32 v179, 0x31000, v177
	v_add_f32_e32 v18, v18, v164
	global_store_dword v178, v18, s[28:29]
	v_cvt_pk_bf16_f32 v164, v18, v18
	global_store_short v179, v164, s[36:37]
	v_add_f32_e32 v2, v2, v165
	global_store_dword v178, v2, s[28:29] offset:128
	v_cvt_pk_bf16_f32 v165, v2, v2
	global_store_short v179, v165, s[36:37] offset:64
	v_add_u32_e32 v178, 0x63000, v176
	v_add_u32_e32 v179, 0x31800, v177
	v_add_f32_e32 v19, v19, v166
	global_store_dword v178, v19, s[28:29]
	v_cvt_pk_bf16_f32 v166, v19, v19
	global_store_short v179, v166, s[36:37]
	v_add_f32_e32 v3, v3, v167
	global_store_dword v178, v3, s[28:29] offset:128
	v_cvt_pk_bf16_f32 v167, v3, v3
	global_store_short v179, v167, s[36:37] offset:64
	v_add_u32_e32 v178, 0x68000, v176
	v_add_u32_e32 v179, 0x34000, v177
	v_add_f32_e32 v20, v20, v168
	global_store_dword v178, v20, s[28:29]
	v_cvt_pk_bf16_f32 v168, v20, v20
	global_store_short v179, v168, s[36:37]
	v_add_f32_e32 v4, v4, v169
	global_store_dword v178, v4, s[28:29] offset:128
	v_cvt_pk_bf16_f32 v169, v4, v4
	global_store_short v179, v169, s[36:37] offset:64
	v_add_u32_e32 v178, 0x69000, v176
	v_add_u32_e32 v179, 0x34800, v177
	v_add_f32_e32 v21, v21, v170
	global_store_dword v178, v21, s[28:29]
	v_cvt_pk_bf16_f32 v170, v21, v21
	global_store_short v179, v170, s[36:37]
	v_add_f32_e32 v5, v5, v171
	global_store_dword v178, v5, s[28:29] offset:128
	v_cvt_pk_bf16_f32 v171, v5, v5
	global_store_short v179, v171, s[36:37] offset:64
	v_add_u32_e32 v178, 0x6a000, v176
	v_add_u32_e32 v179, 0x35000, v177
	v_add_f32_e32 v22, v22, v172
	global_store_dword v178, v22, s[28:29]
	v_cvt_pk_bf16_f32 v172, v22, v22
	global_store_short v179, v172, s[36:37]
	v_add_f32_e32 v6, v6, v173
	global_store_dword v178, v6, s[28:29] offset:128
	v_cvt_pk_bf16_f32 v173, v6, v6
	global_store_short v179, v173, s[36:37] offset:64
	v_add_u32_e32 v178, 0x6b000, v176
	v_add_u32_e32 v179, 0x35800, v177
	v_add_f32_e32 v23, v23, v174
	global_store_dword v178, v23, s[28:29]
	v_cvt_pk_bf16_f32 v174, v23, v23
	global_store_short v179, v174, s[36:37]
	v_add_f32_e32 v7, v7, v175
	global_store_dword v178, v7, s[28:29] offset:128
	v_cvt_pk_bf16_f32 v175, v7, v7
	global_store_short v179, v175, s[36:37] offset:64
	v_add_u32_e32 v178, 0x70000, v176
	v_add_u32_e32 v179, 0x38000, v177
	v_add_f32_e32 v24, v24, v184
	global_store_dword v178, v24, s[28:29]
	v_cvt_pk_bf16_f32 v184, v24, v24
	global_store_short v179, v184, s[36:37]
	v_add_f32_e32 v8, v8, v185
	global_store_dword v178, v8, s[28:29] offset:128
	v_cvt_pk_bf16_f32 v185, v8, v8
	global_store_short v179, v185, s[36:37] offset:64
	v_add_u32_e32 v178, 0x71000, v176
	v_add_u32_e32 v179, 0x38800, v177
	v_add_f32_e32 v25, v25, v186
	global_store_dword v178, v25, s[28:29]
	v_cvt_pk_bf16_f32 v186, v25, v25
	global_store_short v179, v186, s[36:37]
	v_add_f32_e32 v9, v9, v187
	global_store_dword v178, v9, s[28:29] offset:128
	v_cvt_pk_bf16_f32 v187, v9, v9
	global_store_short v179, v187, s[36:37] offset:64
	v_add_u32_e32 v178, 0x72000, v176
	v_add_u32_e32 v179, 0x39000, v177
	v_add_f32_e32 v26, v26, v190
	global_store_dword v178, v26, s[28:29]
	v_cvt_pk_bf16_f32 v190, v26, v26
	global_store_short v179, v190, s[36:37]
	v_add_f32_e32 v10, v10, v191
	global_store_dword v178, v10, s[28:29] offset:128
	v_cvt_pk_bf16_f32 v191, v10, v10
	global_store_short v179, v191, s[36:37] offset:64
	v_add_u32_e32 v178, 0x73000, v176
	v_add_u32_e32 v179, 0x39800, v177
	v_add_f32_e32 v27, v27, v192
	global_store_dword v178, v27, s[28:29]
	v_cvt_pk_bf16_f32 v192, v27, v27
	global_store_short v179, v192, s[36:37]
	v_add_f32_e32 v11, v11, v193
	global_store_dword v178, v11, s[28:29] offset:128
	v_cvt_pk_bf16_f32 v193, v11, v11
	global_store_short v179, v193, s[36:37] offset:64
	v_add_u32_e32 v178, 0x78000, v176
	v_add_u32_e32 v179, 0x3c000, v177
	v_add_f32_e32 v28, v28, v194
	global_store_dword v178, v28, s[28:29]
	v_cvt_pk_bf16_f32 v194, v28, v28
	global_store_short v179, v194, s[36:37]
	v_add_f32_e32 v12, v12, v195
	global_store_dword v178, v12, s[28:29] offset:128
	v_cvt_pk_bf16_f32 v195, v12, v12
	global_store_short v179, v195, s[36:37] offset:64
	v_add_u32_e32 v178, 0x79000, v176
	v_add_u32_e32 v179, 0x3c800, v177
	v_add_f32_e32 v29, v29, v196
	global_store_dword v178, v29, s[28:29]
	v_cvt_pk_bf16_f32 v196, v29, v29
	global_store_short v179, v196, s[36:37]
	v_add_f32_e32 v13, v13, v197
	global_store_dword v178, v13, s[28:29] offset:128
	v_cvt_pk_bf16_f32 v197, v13, v13
	global_store_short v179, v197, s[36:37] offset:64
	v_add_u32_e32 v178, 0x7a000, v176
	v_add_u32_e32 v179, 0x3d000, v177
	v_add_f32_e32 v30, v30, v198
	global_store_dword v178, v30, s[28:29]
	v_cvt_pk_bf16_f32 v198, v30, v30
	global_store_short v179, v198, s[36:37]
	v_add_f32_e32 v14, v14, v199
	global_store_dword v178, v14, s[28:29] offset:128
	v_cvt_pk_bf16_f32 v199, v14, v14
	global_store_short v179, v199, s[36:37] offset:64
	v_add_u32_e32 v178, 0x7b000, v176
	v_add_u32_e32 v179, 0x3d800, v177
	v_add_f32_e32 v31, v31, v200
	global_store_dword v178, v31, s[28:29]
	v_cvt_pk_bf16_f32 v200, v31, v31
	global_store_short v179, v200, s[36:37]
	v_add_f32_e32 v15, v15, v201
	global_store_dword v178, v15, s[28:29] offset:128
	v_cvt_pk_bf16_f32 v201, v15, v15
	global_store_short v179, v201, s[36:37] offset:64
	s_load_dword s3, s[4:5], 0x0
	s_waitcnt lgkmcnt(0)
	s_add_i32 s2, s3, s2
	s_cmpk_gt_i32 s2, 0x1ff
	s_cbranch_scc0 .LBB0_95

; DI int TID() { int t = threadIdx.x; asm volatile("" : "+v"(t)); return t; }
; #define ZERO_ACCM(a, MT) _Pragma("unroll") for (int _m = 0; _m < MT; ++_m) _Pragma("unroll") for (int _n = 0; _n < 2; ++_n) _Pragma("unroll") for (int _i = 0; _i < 16; ++_i) a[_m][_n][_i] = 0.f;
; template <bool NORM, bool DEEP, int MTW, int KSEG, class HOOK>
; DI void gemm_core_h(const bfu* __restrict__ A, int lda, const bfu* __restrict__ Bt, int ldb, int K, int m0, int n0,
;                     f32x16 (&acc)[MTW][2], char* smem, HOOK hook) {
;     ...
;   const int tid = TID(), lane = tid & 63, w = tid >> 6, r = lane & 31, hh = lane >> 5;
;   const int wm = w >> 1, wn = w & 1;
;   const int lrow = tid >> 3, lkc = tid & 7;
;   const unsigned aoff = (unsigned)((m0 + lrow) * lda + lkc * 8);
;   const unsigned boff = (unsigned)((n0 + lrow) * ldb + lkc * 8);
;     ...
;   u32x4 ra0[NA], rb0[4], ra1[NA], rb1[4];
;   float ssq[NA];
; #pragma unroll
;   for (int j = 0; j < NA; ++j) ssq[j] = 0.f;
;   const int nk = K >> 6;
; #pragma unroll
;   for (int j = 0; j < NA; ++j) ra0[j] = *(const u32x4*)AP_(j, 0);
; #pragma unroll
;   for (int j = 0; j < 4; ++j) rb0[j] = *(const u32x4*)BP_(j, 0);
; DI void phase_resid(const Params& p, const bfu* A, int lda, const bfu* Bt, int K, char* smem) {
;     ...
;     int tm, tn; map_tile(id, 8, tm, tn);
;     const int m0 = tm * 256, n0 = tn * 128;
;     f32x16 acc[4][2]; ZERO_ACCM(acc, 4)
;     gemm_core<false, false, 4>(A, lda, Bt, K, K, m0, n0, acc, smem);
.LBB0_127:
	s_ashr_i32 s4, s2, 31
	s_ashr_i32 s3, s2, 3
	s_lshr_b32 s4, s4, 26
	s_add_i32 s4, s3, s4
	s_andn2_b32 s4, s4, 63
	s_lshl_b32 s6, s2, 3
	s_sub_i32 s3, s3, s4
	s_and_b32 s6, s6, 56
	s_and_b32 s5, s3, 7
	s_or_b32 s4, s4, s6
	s_or_b32 s4, s4, s5
	s_lshl_b32 s5, s3, 4
	v_mov_b32_e32 v4, v224
	s_lshl_b32 s3, s4, 8
	s_and_b32 s4, s5, 0xffffff80
	v_readlane_b32 s16, v253, 48
	v_ashrrev_i32_e32 v5, 3, v4
	v_lshlrev_b32_e32 v1, 3, v4
	v_and_b32_e32 v6, 56, v1
	v_add_u32_e32 v1, s4, v5
	v_lshl_or_b32 v178, v1, 10, v6
	v_add_u32_e32 v0, s3, v5
	v_add_u32_e32 v188, 0x18000, v178
	v_readlane_b32 s22, v253, 54
	v_readlane_b32 s23, v253, 55
	v_lshl_or_b32 v176, v0, 10, v6
	v_mov_b32_e32 v179, v189
	v_lshl_add_u64 v[0:1], v[188:189], 1, s[22:23]
	v_add_u32_e32 v188, 0x10000, v178
	v_lshl_add_u64 v[2:3], v[188:189], 1, s[22:23]
	v_add_u32_e32 v188, 0x8000, v178
	global_load_dwordx4 v[132:135], v[0:1], off
	global_load_dwordx4 v[128:131], v[2:3], off
	v_lshl_add_u64 v[0:1], v[188:189], 1, s[22:23]
	v_lshl_add_u64 v[2:3], v[178:179], 1, s[22:23]
	v_mov_b32_e32 v177, v189
	v_add_u32_e32 v188, 0x8000, v176
	global_load_dwordx4 v[136:139], v[0:1], off
	global_load_dwordx4 v[140:143], v[2:3], off
	v_lshl_add_u64 v[0:1], v[176:177], 1, s[76:77]
	v_lshl_add_u64 v[2:3], v[188:189], 1, s[76:77]
	v_add_u32_e32 v188, 0x10000, v176
	global_load_dwordx4 v[148:151], v[0:1], off
	global_load_dwordx4 v[144:147], v[2:3], off
	v_lshl_add_u64 v[0:1], v[188:189], 1, s[76:77]
	v_add_u32_e32 v188, 0x18000, v176
	v_lshl_add_u64 v[2:3], v[188:189], 1, s[76:77]
	v_add_u32_e32 v188, 0x20000, v176
	global_load_dwordx4 v[156:159], v[0:1], off
	global_load_dwordx4 v[152:155], v[2:3], off
	v_lshl_add_u64 v[0:1], v[188:189], 1, s[76:77]
	v_add_u32_e32 v188, 0x28000, v176
	v_lshl_add_u64 v[2:3], v[188:189], 1, s[76:77]
	v_add_u32_e32 v188, 0x30000, v176
	global_load_dwordx4 v[164:167], v[0:1], off
	global_load_dwordx4 v[160:163], v[2:3], off
	v_lshl_add_u64 v[0:1], v[188:189], 1, s[76:77]
	v_add_u32_e32 v188, 0x38000, v176
	v_lshl_add_u64 v[2:3], v[188:189], 1, s[76:77]
	global_load_dwordx4 v[168:171], v[0:1], off
	global_load_dwordx4 v[172:175], v[2:3], off
	v_lshrrev_b32_e32 v2, 1, v4
	v_and_b32_e32 v0, 0x5f, v4
	v_and_b32_e32 v2, 16, v2
	s_movk_i32 s5, 0x90
	v_mad_u32_u24 v182, v0, s5, v2
	v_and_b32_e32 v0, 0xfffff9f, v4
	v_mul_lo_u32 v3, v0, s5
	v_or_b32_e32 v0, 0x60, v4
	v_lshlrev_b32_e32 v1, 1, v6
	v_mul_lo_u32 v5, v5, s5
	v_mul_lo_u32 v4, v0, s5
	v_mov_b32_e32 v0, 0
	s_mov_b32 s5, 0
	v_add_u32_e32 v183, v1, v5
	v_add_u32_e32 v179, v2, v3
	v_add_u32_e32 v177, v2, v4
	v_mov_b32_e32 v1, v0
	v_mov_b32_e32 v2, v0
	v_mov_b32_e32 v3, v0
	v_mov_b32_e32 v4, v0
	v_mov_b32_e32 v5, v0
	v_mov_b32_e32 v6, v0
	v_mov_b32_e32 v7, v0
	v_mov_b32_e32 v8, v0
	v_mov_b32_e32 v9, v0
	v_mov_b32_e32 v10, v0
	v_mov_b32_e32 v11, v0
	v_mov_b32_e32 v12, v0
	v_mov_b32_e32 v13, v0
	v_mov_b32_e32 v14, v0
	v_mov_b32_e32 v15, v0
	v_mov_b32_e32 v16, v0
	v_mov_b32_e32 v17, v0
	v_mov_b32_e32 v18, v0
	v_mov_b32_e32 v19, v0
	v_mov_b32_e32 v20, v0
	v_mov_b32_e32 v21, v0
	v_mov_b32_e32 v22, v0
	v_mov_b32_e32 v23, v0
	v_mov_b32_e32 v24, v0
	v_mov_b32_e32 v25, v0
	v_mov_b32_e32 v26, v0
	v_mov_b32_e32 v27, v0
	v_mov_b32_e32 v28, v0
	v_mov_b32_e32 v29, v0
	v_mov_b32_e32 v30, v0
	v_mov_b32_e32 v31, v0
	v_mov_b32_e32 v32, v0
	v_mov_b32_e32 v33, v0
	v_mov_b32_e32 v34, v0
	v_mov_b32_e32 v35, v0
	v_mov_b32_e32 v36, v0
	v_mov_b32_e32 v37, v0
	v_mov_b32_e32 v38, v0
	v_mov_b32_e32 v39, v0
	v_mov_b32_e32 v40, v0
	v_mov_b32_e32 v41, v0
	v_mov_b32_e32 v42, v0
	v_mov_b32_e32 v43, v0
	v_mov_b32_e32 v44, v0
	v_mov_b32_e32 v45, v0
	v_mov_b32_e32 v46, v0
	v_mov_b32_e32 v47, v0
	v_mov_b32_e32 v48, v0
	v_mov_b32_e32 v49, v0
	v_mov_b32_e32 v50, v0
	v_mov_b32_e32 v51, v0
	v_mov_b32_e32 v52, v0
	v_mov_b32_e32 v53, v0
	v_mov_b32_e32 v54, v0
	v_mov_b32_e32 v55, v0
	v_mov_b32_e32 v56, v0
	v_mov_b32_e32 v57, v0
	v_mov_b32_e32 v58, v0
	v_mov_b32_e32 v59, v0
	v_mov_b32_e32 v60, v0
	v_mov_b32_e32 v61, v0
	v_mov_b32_e32 v62, v0
	v_mov_b32_e32 v63, v0
	v_mov_b32_e32 v64, v0
	v_mov_b32_e32 v65, v0
	v_mov_b32_e32 v66, v0
	v_mov_b32_e32 v67, v0
	v_mov_b32_e32 v68, v0
	v_mov_b32_e32 v69, v0
	v_mov_b32_e32 v70, v0
	v_mov_b32_e32 v71, v0
	s_waitcnt vmcnt(17)
	v_mov_b32_e32 v72, v0
	v_mov_b32_e32 v73, v0
	v_mov_b32_e32 v74, v0
	v_mov_b32_e32 v75, v0
	s_waitcnt vmcnt(16)
	v_mov_b32_e32 v76, v0
	v_mov_b32_e32 v77, v0
	v_mov_b32_e32 v78, v0
	v_mov_b32_e32 v79, v0
	s_waitcnt vmcnt(14)
	v_mov_b32_e32 v80, v0
	v_mov_b32_e32 v81, v0
	v_mov_b32_e32 v82, v0
	v_mov_b32_e32 v83, v0
	v_mov_b32_e32 v84, v0
	v_mov_b32_e32 v85, v0
	v_mov_b32_e32 v86, v0
	v_mov_b32_e32 v87, v0
	s_waitcnt vmcnt(13)
	v_mov_b32_e32 v88, v0
	v_mov_b32_e32 v89, v0
	v_mov_b32_e32 v90, v0
	v_mov_b32_e32 v91, v0
	s_waitcnt vmcnt(12)
	v_mov_b32_e32 v92, v0
	v_mov_b32_e32 v93, v0
	v_mov_b32_e32 v94, v0
	v_mov_b32_e32 v95, v0
	v_mov_b32_e32 v96, v0
	v_mov_b32_e32 v97, v0
	v_mov_b32_e32 v98, v0
	v_mov_b32_e32 v99, v0
	v_mov_b32_e32 v100, v0
	v_mov_b32_e32 v101, v0
	v_mov_b32_e32 v102, v0
	v_mov_b32_e32 v103, v0
	v_mov_b32_e32 v104, v0
	v_mov_b32_e32 v105, v0
	v_mov_b32_e32 v106, v0
	v_mov_b32_e32 v107, v0
	v_mov_b32_e32 v108, v0
	v_mov_b32_e32 v109, v0
	v_mov_b32_e32 v110, v0
	v_mov_b32_e32 v111, v0
	v_mov_b32_e32 v112, v0
	v_mov_b32_e32 v113, v0
	v_mov_b32_e32 v114, v0
	v_mov_b32_e32 v115, v0
	v_mov_b32_e32 v116, v0
	v_mov_b32_e32 v117, v0
	v_mov_b32_e32 v118, v0
	v_mov_b32_e32 v119, v0
	v_mov_b32_e32 v120, v0
	v_mov_b32_e32 v121, v0
	v_mov_b32_e32 v122, v0
	v_mov_b32_e32 v123, v0
	v_mov_b32_e32 v124, v0
	v_mov_b32_e32 v125, v0
	v_mov_b32_e32 v126, v0
	v_mov_b32_e32 v127, v0
	v_readlane_b32 s17, v253, 49
	v_readlane_b32 s18, v253, 50
	v_readlane_b32 s19, v253, 51
	v_readlane_b32 s20, v253, 52
	v_readlane_b32 s21, v253, 53
	v_readlane_b32 s24, v253, 56
	v_readlane_b32 s25, v253, 57
	v_readlane_b32 s26, v253, 58
	v_readlane_b32 s27, v253, 59
	v_readlane_b32 s28, v253, 60
	v_readlane_b32 s29, v253, 61
	v_readlane_b32 s30, v253, 62
	v_readlane_b32 s31, v253, 63
	s_waitcnt vmcnt(0)
.LBB0_128:
	s_waitcnt lgkmcnt(0)
	s_barrier
	s_waitcnt vmcnt(11)
	ds_write_b128 v183, v[140:143] offset:36864
	v_add_u32_e32 v188, s5, v178
	v_add_u32_e32 v188, 0x40, v188
	v_lshl_add_u64 v[140:141], v[188:189], 1, s[22:23]
	global_load_dwordx4 v[140:143], v[140:141], off
	s_waitcnt vmcnt(11)
	ds_write_b128 v183, v[136:139] offset:41472
	v_add_u32_e32 v188, s5, v178
	v_add_u32_e32 v188, 0x8040, v188
	v_lshl_add_u64 v[136:137], v[188:189], 1, s[22:23]
	global_load_dwordx4 v[136:139], v[136:137], off
	s_waitcnt vmcnt(11)
	ds_write_b128 v183, v[128:131] offset:46080
	v_add_u32_e32 v188, s5, v178
	v_add_u32_e32 v188, 0x10040, v188
	v_lshl_add_u64 v[128:129], v[188:189], 1, s[22:23]
	global_load_dwordx4 v[128:131], v[128:129], off
	s_waitcnt vmcnt(11)
	ds_write_b128 v183, v[132:135] offset:50688
	v_add_u32_e32 v188, s5, v178
	v_add_u32_e32 v188, 0x18040, v188
	v_lshl_add_u64 v[132:133], v[188:189], 1, s[22:23]
	global_load_dwordx4 v[132:135], v[132:133], off
	s_waitcnt vmcnt(11)
	ds_write_b128 v183, v[148:151]
	v_add_u32_e32 v188, s5, v176
	v_add_u32_e32 v188, 0x40, v188
	v_lshl_add_u64 v[148:149], v[188:189], 1, s[76:77]
	global_load_dwordx4 v[148:151], v[148:149], off
	s_waitcnt vmcnt(11)
	ds_write_b128 v183, v[144:147] offset:4608
	v_add_u32_e32 v188, s5, v176
	v_add_u32_e32 v188, 0x8040, v188
	v_lshl_add_u64 v[144:145], v[188:189], 1, s[76:77]
	global_load_dwordx4 v[144:147], v[144:145], off
	s_waitcnt vmcnt(11)
	ds_write_b128 v183, v[156:159] offset:9216
	v_add_u32_e32 v188, s5, v176
	v_add_u32_e32 v188, 0x10040, v188
	v_lshl_add_u64 v[156:157], v[188:189], 1, s[76:77]
	global_load_dwordx4 v[156:159], v[156:157], off
	s_waitcnt vmcnt(11)
	ds_write_b128 v183, v[152:155] offset:13824
	v_add_u32_e32 v188, s5, v176
	v_add_u32_e32 v188, 0x18040, v188
	v_lshl_add_u64 v[152:153], v[188:189], 1, s[76:77]
	global_load_dwordx4 v[152:155], v[152:153], off
	s_waitcnt vmcnt(11)
	ds_write_b128 v183, v[164:167] offset:18432
	v_add_u32_e32 v188, s5, v176
	v_add_u32_e32 v188, 0x20040, v188
	v_lshl_add_u64 v[164:165], v[188:189], 1, s[76:77]
	global_load_dwordx4 v[164:167], v[164:165], off
	s_waitcnt vmcnt(11)
	ds_write_b128 v183, v[160:163] offset:23040
	v_add_u32_e32 v188, s5, v176
	v_add_u32_e32 v188, 0x28040, v188
	v_lshl_add_u64 v[160:161], v[188:189], 1, s[76:77]
	global_load_dwordx4 v[160:163], v[160:161], off
	s_waitcnt vmcnt(11)
	ds_write_b128 v183, v[168:171] offset:27648
	v_add_u32_e32 v188, s5, v176
	v_add_u32_e32 v188, 0x30040, v188
	v_lshl_add_u64 v[168:169], v[188:189], 1, s[76:77]
	global_load_dwordx4 v[168:171], v[168:169], off
	s_waitcnt vmcnt(11)
	ds_write_b128 v183, v[172:175] offset:32256
	v_add_u32_e32 v188, s5, v176
	v_add_u32_e32 v188, 0x38040, v188
	v_lshl_add_u64 v[172:173], v[188:189], 1, s[76:77]
	global_load_dwordx4 v[172:175], v[172:173], off
	s_waitcnt lgkmcnt(0)
	s_barrier
	ds_read_b128 v[202:205], v182 offset:36864
	ds_read_b128 v[206:209], v182 offset:41472
	ds_read_b128 v[218:221], v179
	ds_read_b128 v[232:235], v179 offset:4608
	s_waitcnt lgkmcnt(1)
	v_mfma_f32_32x32x16_bf16 v[112:127], v[218:221], v[202:205], v[112:127]
	v_mfma_f32_32x32x16_bf16 v[96:111], v[218:221], v[206:209], v[96:111]
	ds_read_b128 v[218:221], v179 offset:9216
	s_waitcnt lgkmcnt(1)
	v_mfma_f32_32x32x16_bf16 v[80:95], v[232:235], v[202:205], v[80:95]
	v_mfma_f32_32x32x16_bf16 v[64:79], v[232:235], v[206:209], v[64:79]
	ds_read_b128 v[232:235], v177
	ds_read_b128 v[210:213], v182 offset:36896
	ds_read_b128 v[214:217], v182 offset:41504
	s_waitcnt lgkmcnt(3)
	v_mfma_f32_32x32x16_bf16 v[48:63], v[218:221], v[202:205], v[48:63]
	v_mfma_f32_32x32x16_bf16 v[32:47], v[218:221], v[206:209], v[32:47]
	ds_read_b128 v[218:221], v179 offset:32
	s_waitcnt lgkmcnt(3)
	v_mfma_f32_32x32x16_bf16 v[16:31], v[232:235], v[202:205], v[16:31]
	v_mfma_f32_32x32x16_bf16 v[0:15], v[232:235], v[206:209], v[0:15]
	ds_read_b128 v[232:235], v179 offset:4640
	s_waitcnt lgkmcnt(1)
	v_mfma_f32_32x32x16_bf16 v[112:127], v[218:221], v[210:213], v[112:127]
	v_mfma_f32_32x32x16_bf16 v[96:111], v[218:221], v[214:217], v[96:111]
	ds_read_b128 v[218:221], v179 offset:9248
	s_waitcnt lgkmcnt(1)
	v_mfma_f32_32x32x16_bf16 v[80:95], v[232:235], v[210:213], v[80:95]
	v_mfma_f32_32x32x16_bf16 v[64:79], v[232:235], v[214:217], v[64:79]
	ds_read_b128 v[232:235], v177 offset:32
	ds_read_b128 v[202:205], v182 offset:36928
	ds_read_b128 v[206:209], v182 offset:41536
	s_waitcnt lgkmcnt(3)
	v_mfma_f32_32x32x16_bf16 v[48:63], v[218:221], v[210:213], v[48:63]
	v_mfma_f32_32x32x16_bf16 v[32:47], v[218:221], v[214:217], v[32:47]
	ds_read_b128 v[218:221], v179 offset:64
	s_waitcnt lgkmcnt(3)
	v_mfma_f32_32x32x16_bf16 v[16:31], v[232:235], v[210:213], v[16:31]
	v_mfma_f32_32x32x16_bf16 v[0:15], v[232:235], v[214:217], v[0:15]
	ds_read_b128 v[232:235], v179 offset:4672
	s_waitcnt lgkmcnt(1)
	v_mfma_f32_32x32x16_bf16 v[112:127], v[218:221], v[202:205], v[112:127]
	v_mfma_f32_32x32x16_bf16 v[96:111], v[218:221], v[206:209], v[96:111]
	ds_read_b128 v[218:221], v179 offset:9280
	s_waitcnt lgkmcnt(1)
	v_mfma_f32_32x32x16_bf16 v[80:95], v[232:235], v[202:205], v[80:95]
	v_mfma_f32_32x32x16_bf16 v[64:79], v[232:235], v[206:209], v[64:79]
	ds_read_b128 v[232:235], v177 offset:64
	ds_read_b128 v[210:213], v182 offset:36960
	ds_read_b128 v[214:217], v182 offset:41568
	s_waitcnt lgkmcnt(3)
	v_mfma_f32_32x32x16_bf16 v[48:63], v[218:221], v[202:205], v[48:63]
	v_mfma_f32_32x32x16_bf16 v[32:47], v[218:221], v[206:209], v[32:47]
	ds_read_b128 v[218:221], v179 offset:96
	s_waitcnt lgkmcnt(3)
	v_mfma_f32_32x32x16_bf16 v[16:31], v[232:235], v[202:205], v[16:31]
	v_mfma_f32_32x32x16_bf16 v[0:15], v[232:235], v[206:209], v[0:15]
	ds_read_b128 v[232:235], v179 offset:4704
	s_waitcnt lgkmcnt(1)
	v_mfma_f32_32x32x16_bf16 v[112:127], v[218:221], v[210:213], v[112:127]
	v_mfma_f32_32x32x16_bf16 v[96:111], v[218:221], v[214:217], v[96:111]
	ds_read_b128 v[218:221], v179 offset:9312
	s_waitcnt lgkmcnt(1)
	v_mfma_f32_32x32x16_bf16 v[80:95], v[232:235], v[210:213], v[80:95]
	v_mfma_f32_32x32x16_bf16 v[64:79], v[232:235], v[214:217], v[64:79]
	ds_read_b128 v[232:235], v177 offset:96
	s_waitcnt lgkmcnt(1)
	v_mfma_f32_32x32x16_bf16 v[48:63], v[218:221], v[210:213], v[48:63]
	v_mfma_f32_32x32x16_bf16 v[32:47], v[218:221], v[214:217], v[32:47]
	s_waitcnt lgkmcnt(0)
	v_mfma_f32_32x32x16_bf16 v[16:31], v[232:235], v[210:213], v[16:31]
	v_mfma_f32_32x32x16_bf16 v[0:15], v[232:235], v[214:217], v[0:15]
	s_add_i32 s5, s5, 64
	s_cmpk_lg_i32 s5, 0x3c0
	s_cbranch_scc1 .LBB0_128
	s_waitcnt vmcnt(0)
	s_waitcnt lgkmcnt(0)
	s_barrier
	s_waitcnt vmcnt(11)
	ds_write_b128 v183, v[148:151]
	s_waitcnt vmcnt(10)
	ds_write_b128 v183, v[144:147] offset:4608
	s_waitcnt vmcnt(9)
	ds_write_b128 v183, v[156:159] offset:9216
	s_waitcnt vmcnt(8)
	ds_write_b128 v183, v[152:155] offset:13824
	s_waitcnt vmcnt(7)
	ds_write_b128 v183, v[164:167] offset:18432
	s_waitcnt vmcnt(6)
	ds_write_b128 v183, v[160:163] offset:23040
	s_waitcnt vmcnt(5)
	ds_write_b128 v183, v[168:171] offset:27648
	s_waitcnt vmcnt(4)
	ds_write_b128 v183, v[172:175] offset:32256
	s_waitcnt vmcnt(3)
	ds_write_b128 v183, v[140:143] offset:36864
	s_waitcnt vmcnt(2)
	ds_write_b128 v183, v[136:139] offset:41472
	s_waitcnt vmcnt(1)
	ds_write_b128 v183, v[128:131] offset:46080
	s_waitcnt vmcnt(0)
	ds_write_b128 v183, v[132:135] offset:50688
	s_waitcnt lgkmcnt(0)
	s_barrier
	ds_read_b128 v[128:131], v182 offset:41472
	ds_read_b128 v[132:135], v182 offset:36864
	ds_read_b128 v[136:139], v182 offset:36896
	ds_read_b128 v[140:143], v179
	ds_read_b128 v[144:147], v179 offset:32
	s_waitcnt lgkmcnt(1)
	v_mfma_f32_32x32x16_bf16 v[112:127], v[140:143], v[132:135], v[112:127]
	v_readlane_b32 s16, v253, 32
	v_readlane_b32 s28, v253, 44
	v_readlane_b32 s29, v253, 45
	v_readlane_b32 s17, v253, 33
	v_readlane_b32 s18, v253, 34
	v_readlane_b32 s19, v253, 35
	v_readlane_b32 s20, v253, 36
	v_mfma_f32_32x32x16_bf16 v[96:111], v[140:143], v[128:131], v[96:111]
	ds_read_b128 v[140:143], v179 offset:4608
	v_readlane_b32 s21, v253, 37
	v_readlane_b32 s22, v253, 38
	v_readlane_b32 s23, v253, 39
	v_readlane_b32 s24, v253, 40
	v_readlane_b32 s25, v253, 41
	v_readlane_b32 s26, v253, 42
	s_waitcnt lgkmcnt(0)
	v_mfma_f32_32x32x16_bf16 v[80:95], v[140:143], v[132:135], v[80:95]
	v_readlane_b32 s27, v253, 43
	v_readlane_b32 s30, v253, 46
	v_readlane_b32 s31, v253, 47
	v_mfma_f32_32x32x16_bf16 v[64:79], v[140:143], v[128:131], v[64:79]
	ds_read_b128 v[140:143], v179 offset:9216
	s_waitcnt lgkmcnt(0)
	v_mfma_f32_32x32x16_bf16 v[48:63], v[140:143], v[132:135], v[48:63]
	v_mfma_f32_32x32x16_bf16 v[32:47], v[140:143], v[128:131], v[32:47]
	ds_read_b128 v[140:143], v177
	ds_read_b128 v[148:151], v177 offset:32
	s_waitcnt lgkmcnt(1)
	v_mfma_f32_32x32x16_bf16 v[16:31], v[140:143], v[132:135], v[16:31]
	ds_read_b128 v[132:135], v179 offset:4640
	v_mfma_f32_32x32x16_bf16 v[0:15], v[140:143], v[128:131], v[0:15]
	ds_read_b128 v[128:131], v182 offset:41504
	s_waitcnt lgkmcnt(1)
	v_mfma_f32_32x32x16_bf16 v[80:95], v[132:135], v[136:139], v[80:95]
	s_waitcnt lgkmcnt(0)
	v_mfma_f32_32x32x16_bf16 v[64:79], v[132:135], v[128:131], v[64:79]
	ds_read_b128 v[132:135], v179 offset:9248
	v_mfma_f32_32x32x16_bf16 v[112:127], v[144:147], v[136:139], v[112:127]
	v_mfma_f32_32x32x16_bf16 v[96:111], v[144:147], v[128:131], v[96:111]
	s_waitcnt lgkmcnt(0)
	v_mfma_f32_32x32x16_bf16 v[48:63], v[132:135], v[136:139], v[48:63]
	v_mfma_f32_32x32x16_bf16 v[32:47], v[132:135], v[128:131], v[32:47]
	v_mfma_f32_32x32x16_bf16 v[16:31], v[148:151], v[136:139], v[16:31]
	v_mfma_f32_32x32x16_bf16 v[0:15], v[148:151], v[128:131], v[0:15]
	ds_read_b128 v[128:131], v182 offset:36928
	ds_read_b128 v[132:135], v182 offset:41536
	ds_read_b128 v[136:139], v179 offset:64
	s_waitcnt lgkmcnt(0)
	v_mfma_f32_32x32x16_bf16 v[112:127], v[136:139], v[128:131], v[112:127]
	v_mfma_f32_32x32x16_bf16 v[96:111], v[136:139], v[132:135], v[96:111]
	ds_read_b128 v[136:139], v179 offset:4672
	s_waitcnt lgkmcnt(0)
	v_mfma_f32_32x32x16_bf16 v[80:95], v[136:139], v[128:131], v[80:95]
	v_mfma_f32_32x32x16_bf16 v[64:79], v[136:139], v[132:135], v[64:79]
	ds_read_b128 v[136:139], v179 offset:9280
	s_waitcnt lgkmcnt(0)
	v_mfma_f32_32x32x16_bf16 v[48:63], v[136:139], v[128:131], v[48:63]
	v_mfma_f32_32x32x16_bf16 v[32:47], v[136:139], v[132:135], v[32:47]
	ds_read_b128 v[136:139], v177 offset:64
	s_waitcnt lgkmcnt(0)
	v_mfma_f32_32x32x16_bf16 v[16:31], v[136:139], v[128:131], v[16:31]
	v_mfma_f32_32x32x16_bf16 v[0:15], v[136:139], v[132:135], v[0:15]
	ds_read_b128 v[128:131], v182 offset:36960
	ds_read_b128 v[132:135], v182 offset:41568
	ds_read_b128 v[136:139], v179 offset:96
	s_waitcnt lgkmcnt(0)
	v_mfma_f32_32x32x16_bf16 v[112:127], v[136:139], v[128:131], v[112:127]
	v_mfma_f32_32x32x16_bf16 v[96:111], v[136:139], v[132:135], v[96:111]
	ds_read_b128 v[136:139], v179 offset:4704
	s_waitcnt lgkmcnt(0)
	v_mfma_f32_32x32x16_bf16 v[80:95], v[136:139], v[128:131], v[80:95]
	v_mfma_f32_32x32x16_bf16 v[64:79], v[136:139], v[132:135], v[64:79]
	ds_read_b128 v[136:139], v179 offset:9312
	s_waitcnt lgkmcnt(0)
	v_mfma_f32_32x32x16_bf16 v[48:63], v[136:139], v[128:131], v[48:63]
	v_mfma_f32_32x32x16_bf16 v[32:47], v[136:139], v[132:135], v[32:47]
	ds_read_b128 v[136:139], v177 offset:96
	s_waitcnt lgkmcnt(0)
	s_barrier
; DI void phase_resid(const Params& p, const bfu* A, int lda, const bfu* Bt, int K, char* smem) {
;     ...
;     EPI_BEGINM(acc, 4)
;       float* xp = p.out + (size_t)row * 1024 + col;
;       float nv = *xp + v; *xp = nv; p.xb[(size_t)row * 1024 + col] = f2bf(nv);
;     EPI_END
	v_mfma_f32_32x32x16_bf16 v[16:31], v[136:139], v[128:131], v[16:31]
	v_mfma_f32_32x32x16_bf16 v[0:15], v[136:139], v[132:135], v[0:15]
	v_add_u32_e32 v176, s3, v180
	v_or_b32_e32 v177, s4, v181
	v_lshlrev_b32_e32 v176, 12, v176
	v_lshl_add_u32 v176, v177, 2, v176
	v_lshrrev_b32_e32 v177, 1, v176
	v_readlane_b32 s4, v254, 38
	v_readlane_b32 s5, v254, 39
	global_load_dword v128, v176, s[28:29]
	global_load_dword v129, v176, s[28:29] offset:128
	v_add_u32_e32 v178, 0x1000, v176
	global_load_dword v130, v178, s[28:29]
	global_load_dword v131, v178, s[28:29] offset:128
	v_add_u32_e32 v178, 0x2000, v176
	global_load_dword v132, v178, s[28:29]
	global_load_dword v133, v178, s[28:29] offset:128
	v_add_u32_e32 v178, 0x3000, v176
	global_load_dword v134, v178, s[28:29]
	global_load_dword v135, v178, s[28:29] offset:128
	v_add_u32_e32 v178, 0x8000, v176
	global_load_dword v136, v178, s[28:29]
	global_load_dword v137, v178, s[28:29] offset:128
	v_add_u32_e32 v178, 0x9000, v176
	global_load_dword v138, v178, s[28:29]
	global_load_dword v139, v178, s[28:29] offset:128
	v_add_u32_e32 v178, 0xa000, v176
	global_load_dword v140, v178, s[28:29]
	global_load_dword v141, v178, s[28:29] offset:128
	v_add_u32_e32 v178, 0xb000, v176
	global_load_dword v142, v178, s[28:29]
	global_load_dword v143, v178, s[28:29] offset:128
	v_add_u32_e32 v178, 0x10000, v176
	global_load_dword v144, v178, s[28:29]
	global_load_dword v145, v178, s[28:29] offset:128
	v_add_u32_e32 v178, 0x11000, v176
	global_load_dword v146, v178, s[28:29]
	global_load_dword v147, v178, s[28:29] offset:128
	v_add_u32_e32 v178, 0x12000, v176
	global_load_dword v148, v178, s[28:29]
	global_load_dword v149, v178, s[28:29] offset:128
	v_add_u32_e32 v178, 0x13000, v176
	global_load_dword v150, v178, s[28:29]
	global_load_dword v151, v178, s[28:29] offset:128
	v_add_u32_e32 v178, 0x18000, v176
	global_load_dword v152, v178, s[28:29]
	global_load_dword v153, v178, s[28:29] offset:128
	v_add_u32_e32 v178, 0x19000, v176
	global_load_dword v154, v178, s[28:29]
	global_load_dword v155, v178, s[28:29] offset:128
	v_add_u32_e32 v178, 0x1a000, v176
	global_load_dword v156, v178, s[28:29]
	global_load_dword v157, v178, s[28:29] offset:128
	v_add_u32_e32 v178, 0x1b000, v176
	global_load_dword v158, v178, s[28:29]
	global_load_dword v159, v178, s[28:29] offset:128
	v_add_u32_e32 v178, 0x20000, v176
	global_load_dword v160, v178, s[28:29]
	global_load_dword v161, v178, s[28:29] offset:128
	v_add_u32_e32 v178, 0x21000, v176
	global_load_dword v162, v178, s[28:29]
	global_load_dword v163, v178, s[28:29] offset:128
	v_add_u32_e32 v178, 0x22000, v176
	global_load_dword v164, v178, s[28:29]
	global_load_dword v165, v178, s[28:29] offset:128
	v_add_u32_e32 v178, 0x23000, v176
	global_load_dword v166, v178, s[28:29]
	global_load_dword v167, v178, s[28:29] offset:128
	v_add_u32_e32 v178, 0x28000, v176
	global_load_dword v168, v178, s[28:29]
	global_load_dword v169, v178, s[28:29] offset:128
	v_add_u32_e32 v178, 0x29000, v176
	global_load_dword v170, v178, s[28:29]
	global_load_dword v171, v178, s[28:29] offset:128
	v_add_u32_e32 v178, 0x2a000, v176
	global_load_dword v172, v178, s[28:29]
	global_load_dword v173, v178, s[28:29] offset:128
	v_add_u32_e32 v178, 0x2b000, v176
	global_load_dword v174, v178, s[28:29]
	global_load_dword v175, v178, s[28:29] offset:128
	v_add_u32_e32 v178, 0x30000, v176
	global_load_dword v184, v178, s[28:29]
	global_load_dword v185, v178, s[28:29] offset:128
	v_add_u32_e32 v178, 0x31000, v176
	global_load_dword v186, v178, s[28:29]
	global_load_dword v187, v178, s[28:29] offset:128
	v_add_u32_e32 v178, 0x32000, v176
	global_load_dword v190, v178, s[28:29]
	global_load_dword v191, v178, s[28:29] offset:128
	v_add_u32_e32 v178, 0x33000, v176
	global_load_dword v192, v178, s[28:29]
	global_load_dword v193, v178, s[28:29] offset:128
	v_add_u32_e32 v178, 0x38000, v176
	global_load_dword v194, v178, s[28:29]
	global_load_dword v195, v178, s[28:29] offset:128
	v_add_u32_e32 v178, 0x39000, v176
	global_load_dword v196, v178, s[28:29]
	global_load_dword v197, v178, s[28:29] offset:128
	v_add_u32_e32 v178, 0x3a000, v176
	global_load_dword v198, v178, s[28:29]
	global_load_dword v199, v178, s[28:29] offset:128
	v_add_u32_e32 v178, 0x3b000, v176
	global_load_dword v200, v178, s[28:29]
	global_load_dword v201, v178, s[28:29] offset:128
	s_waitcnt vmcnt(32)
; DI void phase_resid(const Params& p, const bfu* A, int lda, const bfu* Bt, int K, char* smem) {
;     ...
;     EPI_BEGINM(acc, 4)
;       float* xp = p.out + (size_t)row * 1024 + col;
;       float nv = *xp + v; *xp = nv; p.xb[(size_t)row * 1024 + col] = f2bf(nv);
;     EPI_END
	v_add_f32_e32 v112, v112, v128
	global_store_dword v176, v112, s[28:29]
	v_cvt_pk_bf16_f32 v128, v112, v112
	global_store_short v177, v128, s[36:37]
	v_add_f32_e32 v96, v96, v129
	global_store_dword v176, v96, s[28:29] offset:128
	v_cvt_pk_bf16_f32 v129, v96, v96
	global_store_short v177, v129, s[36:37] offset:64
	v_add_u32_e32 v178, 0x1000, v176
	v_add_u32_e32 v179, 0x800, v177
	v_add_f32_e32 v113, v113, v130
	global_store_dword v178, v113, s[28:29]
	v_cvt_pk_bf16_f32 v130, v113, v113
	global_store_short v179, v130, s[36:37]
	v_add_f32_e32 v97, v97, v131
	global_store_dword v178, v97, s[28:29] offset:128
	v_cvt_pk_bf16_f32 v131, v97, v97
	global_store_short v179, v131, s[36:37] offset:64
	v_add_u32_e32 v178, 0x2000, v176
	v_add_u32_e32 v179, 0x1000, v177
	v_add_f32_e32 v114, v114, v132
	global_store_dword v178, v114, s[28:29]
	v_cvt_pk_bf16_f32 v132, v114, v114
	global_store_short v179, v132, s[36:37]
	v_add_f32_e32 v98, v98, v133
	global_store_dword v178, v98, s[28:29] offset:128
	v_cvt_pk_bf16_f32 v133, v98, v98
	global_store_short v179, v133, s[36:37] offset:64
	v_add_u32_e32 v178, 0x3000, v176
	v_add_u32_e32 v179, 0x1800, v177
	v_add_f32_e32 v115, v115, v134
	global_store_dword v178, v115, s[28:29]
	v_cvt_pk_bf16_f32 v134, v115, v115
	global_store_short v179, v134, s[36:37]
	v_add_f32_e32 v99, v99, v135
	global_store_dword v178, v99, s[28:29] offset:128
	v_cvt_pk_bf16_f32 v135, v99, v99
	global_store_short v179, v135, s[36:37] offset:64
	v_add_u32_e32 v178, 0x8000, v176
	v_add_u32_e32 v179, 0x4000, v177
	v_add_f32_e32 v116, v116, v136
	global_store_dword v178, v116, s[28:29]
	v_cvt_pk_bf16_f32 v136, v116, v116
	global_store_short v179, v136, s[36:37]
	v_add_f32_e32 v100, v100, v137
	global_store_dword v178, v100, s[28:29] offset:128
	v_cvt_pk_bf16_f32 v137, v100, v100
	global_store_short v179, v137, s[36:37] offset:64
	v_add_u32_e32 v178, 0x9000, v176
	v_add_u32_e32 v179, 0x4800, v177
	v_add_f32_e32 v117, v117, v138
	global_store_dword v178, v117, s[28:29]
	v_cvt_pk_bf16_f32 v138, v117, v117
	global_store_short v179, v138, s[36:37]
	v_add_f32_e32 v101, v101, v139
	global_store_dword v178, v101, s[28:29] offset:128
	v_cvt_pk_bf16_f32 v139, v101, v101
	global_store_short v179, v139, s[36:37] offset:64
	v_add_u32_e32 v178, 0xa000, v176
	v_add_u32_e32 v179, 0x5000, v177
	v_add_f32_e32 v118, v118, v140
	global_store_dword v178, v118, s[28:29]
	v_cvt_pk_bf16_f32 v140, v118, v118
	global_store_short v179, v140, s[36:37]
	v_add_f32_e32 v102, v102, v141
	global_store_dword v178, v102, s[28:29] offset:128
	v_cvt_pk_bf16_f32 v141, v102, v102
	global_store_short v179, v141, s[36:37] offset:64
	v_add_u32_e32 v178, 0xb000, v176
	v_add_u32_e32 v179, 0x5800, v177
	v_add_f32_e32 v119, v119, v142
	global_store_dword v178, v119, s[28:29]
	v_cvt_pk_bf16_f32 v142, v119, v119
	global_store_short v179, v142, s[36:37]
	v_add_f32_e32 v103, v103, v143
	global_store_dword v178, v103, s[28:29] offset:128
	v_cvt_pk_bf16_f32 v143, v103, v103
	global_store_short v179, v143, s[36:37] offset:64
	v_add_u32_e32 v178, 0x10000, v176
	v_add_u32_e32 v179, 0x8000, v177
	v_add_f32_e32 v120, v120, v144
	global_store_dword v178, v120, s[28:29]
	v_cvt_pk_bf16_f32 v144, v120, v120
	global_store_short v179, v144, s[36:37]
	v_add_f32_e32 v104, v104, v145
	global_store_dword v178, v104, s[28:29] offset:128
	v_cvt_pk_bf16_f32 v145, v104, v104
	global_store_short v179, v145, s[36:37] offset:64
	v_add_u32_e32 v178, 0x11000, v176
	v_add_u32_e32 v179, 0x8800, v177
	v_add_f32_e32 v121, v121, v146
	global_store_dword v178, v121, s[28:29]
	v_cvt_pk_bf16_f32 v146, v121, v121
	global_store_short v179, v146, s[36:37]
	v_add_f32_e32 v105, v105, v147
	global_store_dword v178, v105, s[28:29] offset:128
	v_cvt_pk_bf16_f32 v147, v105, v105
	global_store_short v179, v147, s[36:37] offset:64
	v_add_u32_e32 v178, 0x12000, v176
	v_add_u32_e32 v179, 0x9000, v177
	v_add_f32_e32 v122, v122, v148
	global_store_dword v178, v122, s[28:29]
	v_cvt_pk_bf16_f32 v148, v122, v122
	global_store_short v179, v148, s[36:37]
	v_add_f32_e32 v106, v106, v149
	global_store_dword v178, v106, s[28:29] offset:128
	v_cvt_pk_bf16_f32 v149, v106, v106
	global_store_short v179, v149, s[36:37] offset:64
	v_add_u32_e32 v178, 0x13000, v176
	v_add_u32_e32 v179, 0x9800, v177
	v_add_f32_e32 v123, v123, v150
	global_store_dword v178, v123, s[28:29]
	v_cvt_pk_bf16_f32 v150, v123, v123
	global_store_short v179, v150, s[36:37]
	v_add_f32_e32 v107, v107, v151
	global_store_dword v178, v107, s[28:29] offset:128
	v_cvt_pk_bf16_f32 v151, v107, v107
	global_store_short v179, v151, s[36:37] offset:64
	v_add_u32_e32 v178, 0x18000, v176
	v_add_u32_e32 v179, 0xc000, v177
	v_add_f32_e32 v124, v124, v152
	global_store_dword v178, v124, s[28:29]
	v_cvt_pk_bf16_f32 v152, v124, v124
	global_store_short v179, v152, s[36:37]
	v_add_f32_e32 v108, v108, v153
	global_store_dword v178, v108, s[28:29] offset:128
	v_cvt_pk_bf16_f32 v153, v108, v108
	global_store_short v179, v153, s[36:37] offset:64
	v_add_u32_e32 v178, 0x19000, v176
	v_add_u32_e32 v179, 0xc800, v177
	v_add_f32_e32 v125, v125, v154
	global_store_dword v178, v125, s[28:29]
	v_cvt_pk_bf16_f32 v154, v125, v125
	global_store_short v179, v154, s[36:37]
	v_add_f32_e32 v109, v109, v155
	global_store_dword v178, v109, s[28:29] offset:128
	v_cvt_pk_bf16_f32 v155, v109, v109
	global_store_short v179, v155, s[36:37] offset:64
	v_add_u32_e32 v178, 0x1a000, v176
	v_add_u32_e32 v179, 0xd000, v177
	v_add_f32_e32 v126, v126, v156
	global_store_dword v178, v126, s[28:29]
	v_cvt_pk_bf16_f32 v156, v126, v126
	global_store_short v179, v156, s[36:37]
	v_add_f32_e32 v110, v110, v157
; DI void phase_resid(const Params& p, const bfu* A, int lda, const bfu* Bt, int K, char* smem) {
;     ...
;     EPI_BEGINM(acc, 4)
;       float* xp = p.out + (size_t)row * 1024 + col;
;       float nv = *xp + v; *xp = nv; p.xb[(size_t)row * 1024 + col] = f2bf(nv);
;     EPI_END
	global_store_dword v178, v110, s[28:29] offset:128
	v_cvt_pk_bf16_f32 v157, v110, v110
	global_store_short v179, v157, s[36:37] offset:64
	v_add_u32_e32 v178, 0x1b000, v176
	v_add_u32_e32 v179, 0xd800, v177
	v_add_f32_e32 v127, v127, v158
	global_store_dword v178, v127, s[28:29]
	v_cvt_pk_bf16_f32 v158, v127, v127
	global_store_short v179, v158, s[36:37]
	v_add_f32_e32 v111, v111, v159
	global_store_dword v178, v111, s[28:29] offset:128
	v_cvt_pk_bf16_f32 v159, v111, v111
	global_store_short v179, v159, s[36:37] offset:64
	v_add_u32_e32 v178, 0x40000, v176
	global_load_dword v128, v178, s[28:29]
	global_load_dword v129, v178, s[28:29] offset:128
	v_add_u32_e32 v178, 0x41000, v176
	global_load_dword v130, v178, s[28:29]
	global_load_dword v131, v178, s[28:29] offset:128
	v_add_u32_e32 v178, 0x42000, v176
	global_load_dword v132, v178, s[28:29]
	global_load_dword v133, v178, s[28:29] offset:128
	v_add_u32_e32 v178, 0x43000, v176
	global_load_dword v134, v178, s[28:29]
	global_load_dword v135, v178, s[28:29] offset:128
	v_add_u32_e32 v178, 0x48000, v176
	global_load_dword v136, v178, s[28:29]
	global_load_dword v137, v178, s[28:29] offset:128
	v_add_u32_e32 v178, 0x49000, v176
	global_load_dword v138, v178, s[28:29]
	global_load_dword v139, v178, s[28:29] offset:128
	v_add_u32_e32 v178, 0x4a000, v176
	global_load_dword v140, v178, s[28:29]
	global_load_dword v141, v178, s[28:29] offset:128
	v_add_u32_e32 v178, 0x4b000, v176
	global_load_dword v142, v178, s[28:29]
	global_load_dword v143, v178, s[28:29] offset:128
	v_add_u32_e32 v178, 0x50000, v176
	global_load_dword v144, v178, s[28:29]
	global_load_dword v145, v178, s[28:29] offset:128
	v_add_u32_e32 v178, 0x51000, v176
	global_load_dword v146, v178, s[28:29]
	global_load_dword v147, v178, s[28:29] offset:128
	v_add_u32_e32 v178, 0x52000, v176
	global_load_dword v148, v178, s[28:29]
	global_load_dword v149, v178, s[28:29] offset:128
	v_add_u32_e32 v178, 0x53000, v176
	global_load_dword v150, v178, s[28:29]
	global_load_dword v151, v178, s[28:29] offset:128
	v_add_u32_e32 v178, 0x58000, v176
	global_load_dword v152, v178, s[28:29]
	global_load_dword v153, v178, s[28:29] offset:128
	v_add_u32_e32 v178, 0x59000, v176
	global_load_dword v154, v178, s[28:29]
	global_load_dword v155, v178, s[28:29] offset:128
	v_add_u32_e32 v178, 0x5a000, v176
	global_load_dword v156, v178, s[28:29]
	global_load_dword v157, v178, s[28:29] offset:128
	v_add_u32_e32 v178, 0x5b000, v176
	global_load_dword v158, v178, s[28:29]
	global_load_dword v159, v178, s[28:29] offset:128
	s_waitcnt vmcnt(63)
	v_add_u32_e32 v178, 0x20000, v176
	v_add_u32_e32 v179, 0x10000, v177
	v_add_f32_e32 v80, v80, v160
	global_store_dword v178, v80, s[28:29]
	v_cvt_pk_bf16_f32 v160, v80, v80
	global_store_short v179, v160, s[36:37]
	v_add_f32_e32 v64, v64, v161
	global_store_dword v178, v64, s[28:29] offset:128
	v_cvt_pk_bf16_f32 v161, v64, v64
	global_store_short v179, v161, s[36:37] offset:64
	v_add_u32_e32 v178, 0x21000, v176
	v_add_u32_e32 v179, 0x10800, v177
	v_add_f32_e32 v81, v81, v162
	global_store_dword v178, v81, s[28:29]
	v_cvt_pk_bf16_f32 v162, v81, v81
	global_store_short v179, v162, s[36:37]
	v_add_f32_e32 v65, v65, v163
	global_store_dword v178, v65, s[28:29] offset:128
	v_cvt_pk_bf16_f32 v163, v65, v65
	global_store_short v179, v163, s[36:37] offset:64
	v_add_u32_e32 v178, 0x22000, v176
	v_add_u32_e32 v179, 0x11000, v177
	v_add_f32_e32 v82, v82, v164
	global_store_dword v178, v82, s[28:29]
	v_cvt_pk_bf16_f32 v164, v82, v82
	global_store_short v179, v164, s[36:37]
	v_add_f32_e32 v66, v66, v165
	global_store_dword v178, v66, s[28:29] offset:128
	v_cvt_pk_bf16_f32 v165, v66, v66
	global_store_short v179, v165, s[36:37] offset:64
	v_add_u32_e32 v178, 0x23000, v176
	v_add_u32_e32 v179, 0x11800, v177
	v_add_f32_e32 v83, v83, v166
	global_store_dword v178, v83, s[28:29]
	v_cvt_pk_bf16_f32 v166, v83, v83
	global_store_short v179, v166, s[36:37]
	v_add_f32_e32 v67, v67, v167
	global_store_dword v178, v67, s[28:29] offset:128
	v_cvt_pk_bf16_f32 v167, v67, v67
	global_store_short v179, v167, s[36:37] offset:64
	v_add_u32_e32 v178, 0x28000, v176
	v_add_u32_e32 v179, 0x14000, v177
	v_add_f32_e32 v84, v84, v168
	global_store_dword v178, v84, s[28:29]
	v_cvt_pk_bf16_f32 v168, v84, v84
	global_store_short v179, v168, s[36:37]
	v_add_f32_e32 v68, v68, v169
	global_store_dword v178, v68, s[28:29] offset:128
	v_cvt_pk_bf16_f32 v169, v68, v68
	global_store_short v179, v169, s[36:37] offset:64
	v_add_u32_e32 v178, 0x29000, v176
	v_add_u32_e32 v179, 0x14800, v177
	v_add_f32_e32 v85, v85, v170
	global_store_dword v178, v85, s[28:29]
	v_cvt_pk_bf16_f32 v170, v85, v85
	global_store_short v179, v170, s[36:37]
	v_add_f32_e32 v69, v69, v171
	global_store_dword v178, v69, s[28:29] offset:128
	v_cvt_pk_bf16_f32 v171, v69, v69
	global_store_short v179, v171, s[36:37] offset:64
	v_add_u32_e32 v178, 0x2a000, v176
	v_add_u32_e32 v179, 0x15000, v177
	v_add_f32_e32 v86, v86, v172
	global_store_dword v178, v86, s[28:29]
	v_cvt_pk_bf16_f32 v172, v86, v86
	global_store_short v179, v172, s[36:37]
	v_add_f32_e32 v70, v70, v173
	global_store_dword v178, v70, s[28:29] offset:128
	v_cvt_pk_bf16_f32 v173, v70, v70
	global_store_short v179, v173, s[36:37] offset:64
	v_add_u32_e32 v178, 0x2b000, v176
	v_add_u32_e32 v179, 0x15800, v177
	v_add_f32_e32 v87, v87, v174
	global_store_dword v178, v87, s[28:29]
	v_cvt_pk_bf16_f32 v174, v87, v87
	global_store_short v179, v174, s[36:37]
	v_add_f32_e32 v71, v71, v175
	global_store_dword v178, v71, s[28:29] offset:128
	v_cvt_pk_bf16_f32 v175, v71, v71
	global_store_short v179, v175, s[36:37] offset:64
	v_add_u32_e32 v178, 0x30000, v176
; DI void phase_resid(const Params& p, const bfu* A, int lda, const bfu* Bt, int K, char* smem) {
;     ...
;     EPI_BEGINM(acc, 4)
;       float* xp = p.out + (size_t)row * 1024 + col;
;       float nv = *xp + v; *xp = nv; p.xb[(size_t)row * 1024 + col] = f2bf(nv);
;     EPI_END
	v_add_u32_e32 v179, 0x18000, v177
	v_add_f32_e32 v88, v88, v184
	global_store_dword v178, v88, s[28:29]
	v_cvt_pk_bf16_f32 v184, v88, v88
	global_store_short v179, v184, s[36:37]
	v_add_f32_e32 v72, v72, v185
	global_store_dword v178, v72, s[28:29] offset:128
	v_cvt_pk_bf16_f32 v185, v72, v72
	global_store_short v179, v185, s[36:37] offset:64
	v_add_u32_e32 v178, 0x31000, v176
	v_add_u32_e32 v179, 0x18800, v177
	v_add_f32_e32 v89, v89, v186
	global_store_dword v178, v89, s[28:29]
	v_cvt_pk_bf16_f32 v186, v89, v89
	global_store_short v179, v186, s[36:37]
	v_add_f32_e32 v73, v73, v187
	global_store_dword v178, v73, s[28:29] offset:128
	v_cvt_pk_bf16_f32 v187, v73, v73
	global_store_short v179, v187, s[36:37] offset:64
	v_add_u32_e32 v178, 0x32000, v176
	v_add_u32_e32 v179, 0x19000, v177
	v_add_f32_e32 v90, v90, v190
	global_store_dword v178, v90, s[28:29]
	v_cvt_pk_bf16_f32 v190, v90, v90
	global_store_short v179, v190, s[36:37]
	v_add_f32_e32 v74, v74, v191
	global_store_dword v178, v74, s[28:29] offset:128
	v_cvt_pk_bf16_f32 v191, v74, v74
	global_store_short v179, v191, s[36:37] offset:64
	v_add_u32_e32 v178, 0x33000, v176
	v_add_u32_e32 v179, 0x19800, v177
	v_add_f32_e32 v91, v91, v192
	global_store_dword v178, v91, s[28:29]
	v_cvt_pk_bf16_f32 v192, v91, v91
	global_store_short v179, v192, s[36:37]
	v_add_f32_e32 v75, v75, v193
	global_store_dword v178, v75, s[28:29] offset:128
	v_cvt_pk_bf16_f32 v193, v75, v75
	global_store_short v179, v193, s[36:37] offset:64
	v_add_u32_e32 v178, 0x38000, v176
	v_add_u32_e32 v179, 0x1c000, v177
	v_add_f32_e32 v92, v92, v194
	global_store_dword v178, v92, s[28:29]
	v_cvt_pk_bf16_f32 v194, v92, v92
	global_store_short v179, v194, s[36:37]
	v_add_f32_e32 v76, v76, v195
	global_store_dword v178, v76, s[28:29] offset:128
	v_cvt_pk_bf16_f32 v195, v76, v76
	global_store_short v179, v195, s[36:37] offset:64
	v_add_u32_e32 v178, 0x39000, v176
	v_add_u32_e32 v179, 0x1c800, v177
	v_add_f32_e32 v93, v93, v196
	global_store_dword v178, v93, s[28:29]
	v_cvt_pk_bf16_f32 v196, v93, v93
	global_store_short v179, v196, s[36:37]
	v_add_f32_e32 v77, v77, v197
	global_store_dword v178, v77, s[28:29] offset:128
	v_cvt_pk_bf16_f32 v197, v77, v77
	global_store_short v179, v197, s[36:37] offset:64
	v_add_u32_e32 v178, 0x3a000, v176
	v_add_u32_e32 v179, 0x1d000, v177
	v_add_f32_e32 v94, v94, v198
	global_store_dword v178, v94, s[28:29]
	v_cvt_pk_bf16_f32 v198, v94, v94
	global_store_short v179, v198, s[36:37]
	v_add_f32_e32 v78, v78, v199
	global_store_dword v178, v78, s[28:29] offset:128
	v_cvt_pk_bf16_f32 v199, v78, v78
	global_store_short v179, v199, s[36:37] offset:64
	v_add_u32_e32 v178, 0x3b000, v176
	v_add_u32_e32 v179, 0x1d800, v177
	v_add_f32_e32 v95, v95, v200
	global_store_dword v178, v95, s[28:29]
	v_cvt_pk_bf16_f32 v200, v95, v95
	global_store_short v179, v200, s[36:37]
	v_add_f32_e32 v79, v79, v201
	global_store_dword v178, v79, s[28:29] offset:128
	v_cvt_pk_bf16_f32 v201, v79, v79
	global_store_short v179, v201, s[36:37] offset:64
	v_add_u32_e32 v178, 0x60000, v176
	global_load_dword v160, v178, s[28:29]
	global_load_dword v161, v178, s[28:29] offset:128
	v_add_u32_e32 v178, 0x61000, v176
	global_load_dword v162, v178, s[28:29]
	global_load_dword v163, v178, s[28:29] offset:128
	v_add_u32_e32 v178, 0x62000, v176
	global_load_dword v164, v178, s[28:29]
	global_load_dword v165, v178, s[28:29] offset:128
	v_add_u32_e32 v178, 0x63000, v176
	global_load_dword v166, v178, s[28:29]
	global_load_dword v167, v178, s[28:29] offset:128
	v_add_u32_e32 v178, 0x68000, v176
	global_load_dword v168, v178, s[28:29]
	global_load_dword v169, v178, s[28:29] offset:128
	v_add_u32_e32 v178, 0x69000, v176
	global_load_dword v170, v178, s[28:29]
	global_load_dword v171, v178, s[28:29] offset:128
	v_add_u32_e32 v178, 0x6a000, v176
	global_load_dword v172, v178, s[28:29]
	global_load_dword v173, v178, s[28:29] offset:128
	v_add_u32_e32 v178, 0x6b000, v176
	global_load_dword v174, v178, s[28:29]
	global_load_dword v175, v178, s[28:29] offset:128
	v_add_u32_e32 v178, 0x70000, v176
	global_load_dword v184, v178, s[28:29]
	global_load_dword v185, v178, s[28:29] offset:128
	v_add_u32_e32 v178, 0x71000, v176
	global_load_dword v186, v178, s[28:29]
	global_load_dword v187, v178, s[28:29] offset:128
	v_add_u32_e32 v178, 0x72000, v176
	global_load_dword v190, v178, s[28:29]
	global_load_dword v191, v178, s[28:29] offset:128
	v_add_u32_e32 v178, 0x73000, v176
	global_load_dword v192, v178, s[28:29]
	global_load_dword v193, v178, s[28:29] offset:128
	v_add_u32_e32 v178, 0x78000, v176
	global_load_dword v194, v178, s[28:29]
	global_load_dword v195, v178, s[28:29] offset:128
	v_add_u32_e32 v178, 0x79000, v176
	global_load_dword v196, v178, s[28:29]
	global_load_dword v197, v178, s[28:29] offset:128
	v_add_u32_e32 v178, 0x7a000, v176
	global_load_dword v198, v178, s[28:29]
	global_load_dword v199, v178, s[28:29] offset:128
	v_add_u32_e32 v178, 0x7b000, v176
	global_load_dword v200, v178, s[28:29]
	global_load_dword v201, v178, s[28:29] offset:128
	s_waitcnt vmcnt(63)
; DI void phase_resid(const Params& p, const bfu* A, int lda, const bfu* Bt, int K, char* smem) {
;     ...
;     EPI_BEGINM(acc, 4)
;       float* xp = p.out + (size_t)row * 1024 + col;
;       float nv = *xp + v; *xp = nv; p.xb[(size_t)row * 1024 + col] = f2bf(nv);
;     EPI_END
	v_add_u32_e32 v178, 0x40000, v176
	v_add_u32_e32 v179, 0x20000, v177
	v_add_f32_e32 v48, v48, v128
	global_store_dword v178, v48, s[28:29]
	v_cvt_pk_bf16_f32 v128, v48, v48
	global_store_short v179, v128, s[36:37]
	v_add_f32_e32 v32, v32, v129
	global_store_dword v178, v32, s[28:29] offset:128
	v_cvt_pk_bf16_f32 v129, v32, v32
	global_store_short v179, v129, s[36:37] offset:64
	v_add_u32_e32 v178, 0x41000, v176
	v_add_u32_e32 v179, 0x20800, v177
	v_add_f32_e32 v49, v49, v130
	global_store_dword v178, v49, s[28:29]
	v_cvt_pk_bf16_f32 v130, v49, v49
	global_store_short v179, v130, s[36:37]
	v_add_f32_e32 v33, v33, v131
	global_store_dword v178, v33, s[28:29] offset:128
	v_cvt_pk_bf16_f32 v131, v33, v33
	global_store_short v179, v131, s[36:37] offset:64
	v_add_u32_e32 v178, 0x42000, v176
	v_add_u32_e32 v179, 0x21000, v177
	v_add_f32_e32 v50, v50, v132
	global_store_dword v178, v50, s[28:29]
	v_cvt_pk_bf16_f32 v132, v50, v50
	global_store_short v179, v132, s[36:37]
	v_add_f32_e32 v34, v34, v133
	global_store_dword v178, v34, s[28:29] offset:128
	v_cvt_pk_bf16_f32 v133, v34, v34
	global_store_short v179, v133, s[36:37] offset:64
	v_add_u32_e32 v178, 0x43000, v176
	v_add_u32_e32 v179, 0x21800, v177
	v_add_f32_e32 v51, v51, v134
	global_store_dword v178, v51, s[28:29]
	v_cvt_pk_bf16_f32 v134, v51, v51
	global_store_short v179, v134, s[36:37]
	v_add_f32_e32 v35, v35, v135
	global_store_dword v178, v35, s[28:29] offset:128
	v_cvt_pk_bf16_f32 v135, v35, v35
	global_store_short v179, v135, s[36:37] offset:64
	v_add_u32_e32 v178, 0x48000, v176
	v_add_u32_e32 v179, 0x24000, v177
	v_add_f32_e32 v52, v52, v136
	global_store_dword v178, v52, s[28:29]
	v_cvt_pk_bf16_f32 v136, v52, v52
	global_store_short v179, v136, s[36:37]
	v_add_f32_e32 v36, v36, v137
	global_store_dword v178, v36, s[28:29] offset:128
	v_cvt_pk_bf16_f32 v137, v36, v36
	global_store_short v179, v137, s[36:37] offset:64
	v_add_u32_e32 v178, 0x49000, v176
	v_add_u32_e32 v179, 0x24800, v177
	v_add_f32_e32 v53, v53, v138
	global_store_dword v178, v53, s[28:29]
	v_cvt_pk_bf16_f32 v138, v53, v53
	global_store_short v179, v138, s[36:37]
	v_add_f32_e32 v37, v37, v139
	global_store_dword v178, v37, s[28:29] offset:128
	v_cvt_pk_bf16_f32 v139, v37, v37
	global_store_short v179, v139, s[36:37] offset:64
	v_add_u32_e32 v178, 0x4a000, v176
	v_add_u32_e32 v179, 0x25000, v177
	v_add_f32_e32 v54, v54, v140
	global_store_dword v178, v54, s[28:29]
	v_cvt_pk_bf16_f32 v140, v54, v54
	global_store_short v179, v140, s[36:37]
	v_add_f32_e32 v38, v38, v141
	global_store_dword v178, v38, s[28:29] offset:128
	v_cvt_pk_bf16_f32 v141, v38, v38
	global_store_short v179, v141, s[36:37] offset:64
	v_add_u32_e32 v178, 0x4b000, v176
	v_add_u32_e32 v179, 0x25800, v177
	v_add_f32_e32 v55, v55, v142
	global_store_dword v178, v55, s[28:29]
	v_cvt_pk_bf16_f32 v142, v55, v55
	global_store_short v179, v142, s[36:37]
	v_add_f32_e32 v39, v39, v143
	global_store_dword v178, v39, s[28:29] offset:128
	v_cvt_pk_bf16_f32 v143, v39, v39
	global_store_short v179, v143, s[36:37] offset:64
	v_add_u32_e32 v178, 0x50000, v176
	v_add_u32_e32 v179, 0x28000, v177
	v_add_f32_e32 v56, v56, v144
	global_store_dword v178, v56, s[28:29]
	v_cvt_pk_bf16_f32 v144, v56, v56
	global_store_short v179, v144, s[36:37]
	v_add_f32_e32 v40, v40, v145
	global_store_dword v178, v40, s[28:29] offset:128
	v_cvt_pk_bf16_f32 v145, v40, v40
	global_store_short v179, v145, s[36:37] offset:64
	v_add_u32_e32 v178, 0x51000, v176
	v_add_u32_e32 v179, 0x28800, v177
	v_add_f32_e32 v57, v57, v146
	global_store_dword v178, v57, s[28:29]
	v_cvt_pk_bf16_f32 v146, v57, v57
	global_store_short v179, v146, s[36:37]
	v_add_f32_e32 v41, v41, v147
	global_store_dword v178, v41, s[28:29] offset:128
	v_cvt_pk_bf16_f32 v147, v41, v41
	global_store_short v179, v147, s[36:37] offset:64
	v_add_u32_e32 v178, 0x52000, v176
	v_add_u32_e32 v179, 0x29000, v177
	v_add_f32_e32 v58, v58, v148
	global_store_dword v178, v58, s[28:29]
	v_cvt_pk_bf16_f32 v148, v58, v58
	global_store_short v179, v148, s[36:37]
	v_add_f32_e32 v42, v42, v149
	global_store_dword v178, v42, s[28:29] offset:128
	v_cvt_pk_bf16_f32 v149, v42, v42
	global_store_short v179, v149, s[36:37] offset:64
	v_add_u32_e32 v178, 0x53000, v176
	v_add_u32_e32 v179, 0x29800, v177
	v_add_f32_e32 v59, v59, v150
	global_store_dword v178, v59, s[28:29]
	v_cvt_pk_bf16_f32 v150, v59, v59
	global_store_short v179, v150, s[36:37]
	v_add_f32_e32 v43, v43, v151
	global_store_dword v178, v43, s[28:29] offset:128
	v_cvt_pk_bf16_f32 v151, v43, v43
	global_store_short v179, v151, s[36:37] offset:64
	v_add_u32_e32 v178, 0x58000, v176
	v_add_u32_e32 v179, 0x2c000, v177
	v_add_f32_e32 v60, v60, v152
	global_store_dword v178, v60, s[28:29]
	v_cvt_pk_bf16_f32 v152, v60, v60
	global_store_short v179, v152, s[36:37]
	v_add_f32_e32 v44, v44, v153
	global_store_dword v178, v44, s[28:29] offset:128
	v_cvt_pk_bf16_f32 v153, v44, v44
	global_store_short v179, v153, s[36:37] offset:64
	v_add_u32_e32 v178, 0x59000, v176
	v_add_u32_e32 v179, 0x2c800, v177
	v_add_f32_e32 v61, v61, v154
	global_store_dword v178, v61, s[28:29]
	v_cvt_pk_bf16_f32 v154, v61, v61
	global_store_short v179, v154, s[36:37]
	v_add_f32_e32 v45, v45, v155
	global_store_dword v178, v45, s[28:29] offset:128
	v_cvt_pk_bf16_f32 v155, v45, v45
	global_store_short v179, v155, s[36:37] offset:64
	v_add_u32_e32 v178, 0x5a000, v176
	v_add_u32_e32 v179, 0x2d000, v177
	v_add_f32_e32 v62, v62, v156
	global_store_dword v178, v62, s[28:29]
	v_cvt_pk_bf16_f32 v156, v62, v62
	global_store_short v179, v156, s[36:37]
	v_add_f32_e32 v46, v46, v157
	global_store_dword v178, v46, s[28:29] offset:128
	v_cvt_pk_bf16_f32 v157, v46, v46
	global_store_short v179, v157, s[36:37] offset:64
	v_add_u32_e32 v178, 0x5b000, v176
	v_add_u32_e32 v179, 0x2d800, v177
	v_add_f32_e32 v63, v63, v158
	global_store_dword v178, v63, s[28:29]
	v_cvt_pk_bf16_f32 v158, v63, v63
	global_store_short v179, v158, s[36:37]
	v_add_f32_e32 v47, v47, v159
	global_store_dword v178, v47, s[28:29] offset:128
	v_cvt_pk_bf16_f32 v159, v47, v47
	global_store_short v179, v159, s[36:37] offset:64
	s_waitcnt vmcnt(63)
; #define ZERO_ACCM(a, MT) _Pragma("unroll") for (int _m = 0; _m < MT; ++_m) _Pragma("unroll") for (int _n = 0; _n < 2; ++_n) _Pragma("unroll") for (int _i = 0; _i < 16; ++_i) a[_m][_n][_i] = 0.f;
; DI void phase_resid(const Params& p, const bfu* A, int lda, const bfu* Bt, int K, char* smem) {
;     ...
;   for (int id = blockIdx.x; id < 64 * 8; id += gridDim.x) {
;     int tm, tn; map_tile(id, 8, tm, tn);
;     const int m0 = tm * 256, n0 = tn * 128;
;     f32x16 acc[4][2]; ZERO_ACCM(acc, 4)
;     gemm_core<false, false, 4>(A, lda, Bt, K, K, m0, n0, acc, smem);
;     EPI_BEGINM(acc, 4)
;       float* xp = p.out + (size_t)row * 1024 + col;
;       float nv = *xp + v; *xp = nv; p.xb[(size_t)row * 1024 + col] = f2bf(nv);
;     EPI_END
	v_add_u32_e32 v178, 0x60000, v176
	v_add_u32_e32 v179, 0x30000, v177
	v_add_f32_e32 v16, v16, v160
	global_store_dword v178, v16, s[28:29]
	v_cvt_pk_bf16_f32 v160, v16, v16
	global_store_short v179, v160, s[36:37]
	v_add_f32_e32 v0, v0, v161
	global_store_dword v178, v0, s[28:29] offset:128
	v_cvt_pk_bf16_f32 v161, v0, v0
	global_store_short v179, v161, s[36:37] offset:64
	v_add_u32_e32 v178, 0x61000, v176
	v_add_u32_e32 v179, 0x30800, v177
	v_add_f32_e32 v17, v17, v162
	global_store_dword v178, v17, s[28:29]
	v_cvt_pk_bf16_f32 v162, v17, v17
	global_store_short v179, v162, s[36:37]
	v_add_f32_e32 v1, v1, v163
	global_store_dword v178, v1, s[28:29] offset:128
	v_cvt_pk_bf16_f32 v163, v1, v1
	global_store_short v179, v163, s[36:37] offset:64
	v_add_u32_e32 v178, 0x62000, v176
	v_add_u32_e32 v179, 0x31000, v177
	v_add_f32_e32 v18, v18, v164
	global_store_dword v178, v18, s[28:29]
	v_cvt_pk_bf16_f32 v164, v18, v18
	global_store_short v179, v164, s[36:37]
	v_add_f32_e32 v2, v2, v165
	global_store_dword v178, v2, s[28:29] offset:128
	v_cvt_pk_bf16_f32 v165, v2, v2
	global_store_short v179, v165, s[36:37] offset:64
	v_add_u32_e32 v178, 0x63000, v176
	v_add_u32_e32 v179, 0x31800, v177
	v_add_f32_e32 v19, v19, v166
	global_store_dword v178, v19, s[28:29]
	v_cvt_pk_bf16_f32 v166, v19, v19
	global_store_short v179, v166, s[36:37]
	v_add_f32_e32 v3, v3, v167
	global_store_dword v178, v3, s[28:29] offset:128
	v_cvt_pk_bf16_f32 v167, v3, v3
	global_store_short v179, v167, s[36:37] offset:64
	v_add_u32_e32 v178, 0x68000, v176
	v_add_u32_e32 v179, 0x34000, v177
	v_add_f32_e32 v20, v20, v168
	global_store_dword v178, v20, s[28:29]
	v_cvt_pk_bf16_f32 v168, v20, v20
	global_store_short v179, v168, s[36:37]
	v_add_f32_e32 v4, v4, v169
	global_store_dword v178, v4, s[28:29] offset:128
	v_cvt_pk_bf16_f32 v169, v4, v4
	global_store_short v179, v169, s[36:37] offset:64
	v_add_u32_e32 v178, 0x69000, v176
	v_add_u32_e32 v179, 0x34800, v177
	v_add_f32_e32 v21, v21, v170
	global_store_dword v178, v21, s[28:29]
	v_cvt_pk_bf16_f32 v170, v21, v21
	global_store_short v179, v170, s[36:37]
	v_add_f32_e32 v5, v5, v171
	global_store_dword v178, v5, s[28:29] offset:128
	v_cvt_pk_bf16_f32 v171, v5, v5
	global_store_short v179, v171, s[36:37] offset:64
	v_add_u32_e32 v178, 0x6a000, v176
	v_add_u32_e32 v179, 0x35000, v177
	v_add_f32_e32 v22, v22, v172
	global_store_dword v178, v22, s[28:29]
	v_cvt_pk_bf16_f32 v172, v22, v22
	global_store_short v179, v172, s[36:37]
	v_add_f32_e32 v6, v6, v173
	global_store_dword v178, v6, s[28:29] offset:128
	v_cvt_pk_bf16_f32 v173, v6, v6
	global_store_short v179, v173, s[36:37] offset:64
	v_add_u32_e32 v178, 0x6b000, v176
	v_add_u32_e32 v179, 0x35800, v177
	v_add_f32_e32 v23, v23, v174
	global_store_dword v178, v23, s[28:29]
	v_cvt_pk_bf16_f32 v174, v23, v23
	global_store_short v179, v174, s[36:37]
	v_add_f32_e32 v7, v7, v175
	global_store_dword v178, v7, s[28:29] offset:128
	v_cvt_pk_bf16_f32 v175, v7, v7
	global_store_short v179, v175, s[36:37] offset:64
	v_add_u32_e32 v178, 0x70000, v176
	v_add_u32_e32 v179, 0x38000, v177
	v_add_f32_e32 v24, v24, v184
	global_store_dword v178, v24, s[28:29]
	v_cvt_pk_bf16_f32 v184, v24, v24
	global_store_short v179, v184, s[36:37]
	v_add_f32_e32 v8, v8, v185
	global_store_dword v178, v8, s[28:29] offset:128
	v_cvt_pk_bf16_f32 v185, v8, v8
	global_store_short v179, v185, s[36:37] offset:64
	v_add_u32_e32 v178, 0x71000, v176
	v_add_u32_e32 v179, 0x38800, v177
	v_add_f32_e32 v25, v25, v186
	global_store_dword v178, v25, s[28:29]
	v_cvt_pk_bf16_f32 v186, v25, v25
	global_store_short v179, v186, s[36:37]
	v_add_f32_e32 v9, v9, v187
	global_store_dword v178, v9, s[28:29] offset:128
	v_cvt_pk_bf16_f32 v187, v9, v9
	global_store_short v179, v187, s[36:37] offset:64
	v_add_u32_e32 v178, 0x72000, v176
	v_add_u32_e32 v179, 0x39000, v177
	v_add_f32_e32 v26, v26, v190
	global_store_dword v178, v26, s[28:29]
	v_cvt_pk_bf16_f32 v190, v26, v26
	global_store_short v179, v190, s[36:37]
	v_add_f32_e32 v10, v10, v191
	global_store_dword v178, v10, s[28:29] offset:128
	v_cvt_pk_bf16_f32 v191, v10, v10
	global_store_short v179, v191, s[36:37] offset:64
	v_add_u32_e32 v178, 0x73000, v176
	v_add_u32_e32 v179, 0x39800, v177
	v_add_f32_e32 v27, v27, v192
	global_store_dword v178, v27, s[28:29]
	v_cvt_pk_bf16_f32 v192, v27, v27
	global_store_short v179, v192, s[36:37]
	v_add_f32_e32 v11, v11, v193
	global_store_dword v178, v11, s[28:29] offset:128
	v_cvt_pk_bf16_f32 v193, v11, v11
	global_store_short v179, v193, s[36:37] offset:64
	v_add_u32_e32 v178, 0x78000, v176
	v_add_u32_e32 v179, 0x3c000, v177
	v_add_f32_e32 v28, v28, v194
	global_store_dword v178, v28, s[28:29]
	v_cvt_pk_bf16_f32 v194, v28, v28
	global_store_short v179, v194, s[36:37]
	v_add_f32_e32 v12, v12, v195
	global_store_dword v178, v12, s[28:29] offset:128
	v_cvt_pk_bf16_f32 v195, v12, v12
	global_store_short v179, v195, s[36:37] offset:64
	v_add_u32_e32 v178, 0x79000, v176
	v_add_u32_e32 v179, 0x3c800, v177
	v_add_f32_e32 v29, v29, v196
	global_store_dword v178, v29, s[28:29]
	v_cvt_pk_bf16_f32 v196, v29, v29
	global_store_short v179, v196, s[36:37]
	v_add_f32_e32 v13, v13, v197
	global_store_dword v178, v13, s[28:29] offset:128
	v_cvt_pk_bf16_f32 v197, v13, v13
	global_store_short v179, v197, s[36:37] offset:64
	v_add_u32_e32 v178, 0x7a000, v176
	v_add_u32_e32 v179, 0x3d000, v177
	v_add_f32_e32 v30, v30, v198
	global_store_dword v178, v30, s[28:29]
	v_cvt_pk_bf16_f32 v198, v30, v30
	global_store_short v179, v198, s[36:37]
	v_add_f32_e32 v14, v14, v199
	global_store_dword v178, v14, s[28:29] offset:128
	v_cvt_pk_bf16_f32 v199, v14, v14
	global_store_short v179, v199, s[36:37] offset:64
	v_add_u32_e32 v178, 0x7b000, v176
	v_add_u32_e32 v179, 0x3d800, v177
	v_add_f32_e32 v31, v31, v200
	global_store_dword v178, v31, s[28:29]
	v_cvt_pk_bf16_f32 v200, v31, v31
	global_store_short v179, v200, s[36:37]
	v_add_f32_e32 v15, v15, v201
	global_store_dword v178, v15, s[28:29] offset:128
	v_cvt_pk_bf16_f32 v201, v15, v15
	global_store_short v179, v201, s[36:37] offset:64
	s_load_dword s3, s[4:5], 0x0
	s_waitcnt lgkmcnt(0)
	s_add_i32 s2, s3, s2
	s_cmpk_gt_i32 s2, 0x1ff
	s_cbranch_scc0 .LBB0_127
